# row-wise phases (x rmsnorm, both residual+rmsnorm phases): wave_sum butterflies via DPP quad_perm / row_half_mirror / row_mirror and v_permlane16/32_swap instead of ds_bpermute rounds (same operand pa
# speedup vs baseline: 1.0097x; 1.0031x over previous
.LBB0_306:
	s_waitcnt vmcnt(3)
	v_pk_mul_f32 v[146:147], v[126:127], v[126:127]
	v_pk_mul_f32 v[148:149], v[124:125], v[124:125]
	s_waitcnt vmcnt(0)
	v_mul_f32_e32 v128, v112, v112
	v_pk_mov_b32 v[150:151], v[148:149], v[146:147] op_sel:[1,0]
	v_mov_b32_e32 v149, v147
	v_pk_add_f32 v[146:147], v[150:151], v[148:149]
	v_pk_mul_f32 v[148:149], v[122:123], v[122:123]
	v_pk_mul_f32 v[150:151], v[120:121], v[120:121]
	v_mul_f32_e32 v145, v113, v113
	v_pk_mov_b32 v[152:153], v[150:151], v[148:149] op_sel:[1,0]
	v_mov_b32_e32 v151, v149
	v_pk_add_f32 v[148:149], v[152:153], v[150:151]
	v_pk_add_f32 v[146:147], v[146:147], v[146:147] op_sel:[0,1] op_sel_hi:[1,0]
	v_pk_add_f32 v[148:149], v[148:149], v[148:149] op_sel:[0,1] op_sel_hi:[1,0]
	v_mov_b32_e32 v147, v128
	v_mov_b32_e32 v149, v145
	v_mul_f32_e32 v128, v117, v117
	v_mul_f32_e32 v150, v114, v114
	v_pk_add_f32 v[146:147], v[146:147], v[148:149]
	v_pk_fma_f32 v[148:149], v[116:117], v[116:117], v[128:129] op_sel_hi:[1,1,0]
	v_mul_f32_e32 v128, v119, v119
	v_mul_f32_e32 v152, v115, v115
	v_mov_b32_e32 v149, v150
	v_pk_fma_f32 v[150:151], v[118:119], v[118:119], v[128:129] op_sel_hi:[1,1,0]
	s_nop 0
	v_mov_b32_e32 v151, v152
	v_pk_add_f32 v[148:149], v[148:149], v[150:151]
	s_nop 0
	v_pk_add_f32 v[146:147], v[146:147], v[148:149]
	s_nop 0
	v_add_f32_e32 v128, v146, v147
	s_waitcnt lgkmcnt(0)
	s_nop 1
	v_add_f32_dpp v128, v128, v128 quad_perm:[1,0,3,2] row_mask:0xf bank_mask:0xf
	s_waitcnt lgkmcnt(0)
	s_nop 1
	v_add_f32_dpp v128, v128, v128 quad_perm:[2,3,0,1] row_mask:0xf bank_mask:0xf
	s_waitcnt lgkmcnt(0)
	s_nop 1
	v_add_f32_dpp v128, v128, v128 row_half_mirror row_mask:0xf bank_mask:0xf
	s_waitcnt lgkmcnt(0)
	s_nop 1
	v_add_f32_dpp v128, v128, v128 row_mirror row_mask:0xf bank_mask:0xf
	s_waitcnt lgkmcnt(0)
	v_mov_b32_e32 v145, v128
	s_nop 1
	v_permlane16_swap_b32_e32 v128, v145
	v_add_f32_e32 v128, v128, v145
	s_waitcnt lgkmcnt(0)
	v_mov_b32_e32 v145, v128
	s_nop 1
	v_permlane32_swap_b32_e32 v128, v145
	v_add_f32_e32 v128, v128, v145
	v_fmamk_f32 v128, v128, 0x3a800000, v144
	v_mul_f32_e32 v145, 0x4b800000, v128
	v_cmp_gt_f32_e32 vcc, s1, v128
	s_nop 1
	v_cndmask_b32_e32 v128, v128, v145, vcc
	v_rsq_f32_e32 v128, v128
	s_nop 0
	v_mul_f32_e32 v145, 0x45800000, v128
	v_cndmask_b32_e32 v128, v128, v145, vcc
	s_and_saveexec_b64 s[76:77], s[2:3]
	s_cbranch_execz .LBB0_308
	v_div_scale_f32 v145, s[86:87], v128, v128, 1.0
	v_rcp_f32_e32 v146, v145
	v_div_scale_f32 v147, vcc, 1.0, v128, 1.0
	s_add_u32 s86, s60, s84
	v_fma_f32 v148, -v145, v146, 1.0
	v_fmac_f32_e32 v146, v148, v146
	v_mul_f32_e32 v148, v147, v146
	v_fma_f32 v149, -v145, v148, v147
	v_fmac_f32_e32 v148, v149, v146
	v_fma_f32 v145, -v145, v148, v147
	v_div_fmas_f32 v145, v145, v146, v148
	v_div_fixup_f32 v145, v145, v128, 1.0
	s_addc_u32 s87, s61, s85
	global_store_dword v129, v145, s[86:87]

.LBB0_315:
	v_pk_mul_f32 v[112:113], v[110:111], v[110:111]
	v_pk_mul_f32 v[114:115], v[108:109], v[108:109]
	s_nop 0
	v_pk_mov_b32 v[116:117], v[114:115], v[112:113] op_sel:[1,0]
	v_mov_b32_e32 v115, v113
	v_pk_add_f32 v[112:113], v[116:117], v[114:115]
	v_pk_mul_f32 v[114:115], v[106:107], v[106:107]
	v_pk_add_f32 v[112:113], v[112:113], v[112:113] op_sel_hi:[0,1]
	v_pk_mul_f32 v[116:117], v[104:105], v[104:105]
	v_mul_f32_e32 v112, v100, v100
	v_pk_mov_b32 v[118:119], v[116:117], v[114:115] op_sel:[1,0]
	v_mov_b32_e32 v117, v115
	v_pk_add_f32 v[114:115], v[118:119], v[116:117]
	v_pk_fma_f32 v[116:117], v[100:101], v[100:101], v[112:113] op_sel_hi:[1,1,0]
	v_mul_f32_e32 v112, v102, v102
	v_pk_add_f32 v[114:115], v[114:115], v[114:115] op_sel_hi:[0,1]
	v_pk_fma_f32 v[118:119], v[102:103], v[102:103], v[112:113] op_sel_hi:[1,1,0]
	v_mul_f32_e32 v116, v96, v96
	v_mul_f32_e32 v118, v97, v97
	v_mul_f32_e32 v114, v98, v98
	v_mul_f32_e32 v112, v99, v99
	v_pk_add_f32 v[116:117], v[116:117], v[118:119]
	v_pk_add_f32 v[112:113], v[114:115], v[112:113]
	s_nop 0
	v_pk_add_f32 v[112:113], v[116:117], v[112:113]
	s_nop 0
	v_add_f32_e32 v112, v112, v113
	s_waitcnt lgkmcnt(0)
	s_nop 1
	v_add_f32_dpp v112, v112, v112 quad_perm:[1,0,3,2] row_mask:0xf bank_mask:0xf
	s_waitcnt lgkmcnt(0)
	s_nop 1
	v_add_f32_dpp v112, v112, v112 quad_perm:[2,3,0,1] row_mask:0xf bank_mask:0xf
	s_waitcnt lgkmcnt(0)
	s_nop 1
	v_add_f32_dpp v112, v112, v112 row_half_mirror row_mask:0xf bank_mask:0xf
	s_waitcnt lgkmcnt(0)
	s_nop 1
	v_add_f32_dpp v112, v112, v112 row_mirror row_mask:0xf bank_mask:0xf
	s_waitcnt lgkmcnt(0)
	v_mov_b32_e32 v113, v112
	s_nop 1
	v_permlane16_swap_b32_e32 v112, v113
	v_add_f32_e32 v112, v112, v113
	s_waitcnt lgkmcnt(0)
	v_mov_b32_e32 v113, v112
	s_nop 1
	v_permlane32_swap_b32_e32 v112, v113
	v_add_f32_e32 v112, v112, v113
	v_fmamk_f32 v112, v112, 0x3a800000, v144
	v_cmp_gt_f32_e32 vcc, s1, v112
	s_and_saveexec_b64 s[74:75], s[4:5]
	s_xor_b64 s[74:75], exec, s[74:75]
	s_ashr_i32 s73, s72, 31
	s_or_saveexec_b64 s[74:75], s[74:75]
	v_mul_f32_e32 v113, 0x4b800000, v112
	v_cndmask_b32_e32 v112, v112, v113, vcc
	v_rsq_f32_e32 v112, v112
	v_mov_b64_e32 v[114:115], s[72:73]
	v_mul_f32_e32 v113, 0x45800000, v112
	v_cndmask_b32_e32 v112, v112, v113, vcc
	s_xor_b64 exec, exec, s[74:75]
	s_cbranch_execz .LBB0_319
	v_div_scale_f32 v113, s[76:77], v112, v112, 1.0
	v_rcp_f32_e32 v114, v113
	v_div_scale_f32 v115, vcc, 1.0, v112, 1.0
	s_ashr_i32 s73, s72, 31
	v_fma_f32 v116, -v113, v114, 1.0
	v_fmac_f32_e32 v114, v116, v114
	v_mul_f32_e32 v116, v115, v114
	v_fma_f32 v117, -v113, v116, v115
	v_fmac_f32_e32 v116, v117, v114
	v_fma_f32 v113, -v113, v116, v115
	s_lshl_b64 s[76:77], s[72:73], 2
	v_div_fmas_f32 v113, v113, v114, v116
	s_add_u32 s76, s39, s76
	v_div_fixup_f32 v113, v113, v112, 1.0
	s_addc_u32 s77, s65, s77
	v_mov_b64_e32 v[114:115], s[72:73]
	global_store_dword v129, v113, s[76:77]

.LBB0_320:
	v_pk_mul_f32 v[112:113], v[94:95], v[94:95]
	v_pk_mul_f32 v[114:115], v[92:93], v[92:93]
	s_nop 0
	v_pk_mov_b32 v[116:117], v[114:115], v[112:113] op_sel:[1,0]
	v_mov_b32_e32 v115, v113
	v_pk_add_f32 v[112:113], v[116:117], v[114:115]
	v_pk_mul_f32 v[114:115], v[90:91], v[90:91]
	v_pk_add_f32 v[112:113], v[112:113], v[112:113] op_sel_hi:[0,1]
	v_pk_mul_f32 v[116:117], v[88:89], v[88:89]
	v_mul_f32_e32 v112, v84, v84
	v_pk_mov_b32 v[118:119], v[116:117], v[114:115] op_sel:[1,0]
	v_mov_b32_e32 v117, v115
	v_pk_add_f32 v[114:115], v[118:119], v[116:117]
	v_pk_fma_f32 v[116:117], v[84:85], v[84:85], v[112:113] op_sel_hi:[1,1,0]
	v_mul_f32_e32 v112, v86, v86
	v_pk_add_f32 v[114:115], v[114:115], v[114:115] op_sel_hi:[0,1]
	v_pk_fma_f32 v[118:119], v[86:87], v[86:87], v[112:113] op_sel_hi:[1,1,0]
	v_mul_f32_e32 v116, v80, v80
	v_mul_f32_e32 v118, v81, v81
	v_mul_f32_e32 v114, v82, v82
	v_mul_f32_e32 v112, v83, v83
	v_pk_add_f32 v[116:117], v[116:117], v[118:119]
	v_pk_add_f32 v[112:113], v[114:115], v[112:113]
	s_nop 0
	v_pk_add_f32 v[112:113], v[116:117], v[112:113]
	s_nop 0
	v_add_f32_e32 v112, v112, v113
	s_waitcnt lgkmcnt(0)
	s_nop 1
	v_add_f32_dpp v112, v112, v112 quad_perm:[1,0,3,2] row_mask:0xf bank_mask:0xf
	s_waitcnt lgkmcnt(0)
	s_nop 1
	v_add_f32_dpp v112, v112, v112 quad_perm:[2,3,0,1] row_mask:0xf bank_mask:0xf
	s_waitcnt lgkmcnt(0)
	s_nop 1
	v_add_f32_dpp v112, v112, v112 row_half_mirror row_mask:0xf bank_mask:0xf
	s_waitcnt lgkmcnt(0)
	s_nop 1
	v_add_f32_dpp v112, v112, v112 row_mirror row_mask:0xf bank_mask:0xf
	s_waitcnt lgkmcnt(0)
	v_mov_b32_e32 v113, v112
	s_nop 1
	v_permlane16_swap_b32_e32 v112, v113
	v_add_f32_e32 v112, v112, v113
	s_waitcnt lgkmcnt(0)
	v_mov_b32_e32 v113, v112
	s_nop 1
	v_permlane32_swap_b32_e32 v112, v113
	v_add_f32_e32 v112, v112, v113
	v_fmamk_f32 v112, v112, 0x3a800000, v144
	v_cmp_gt_f32_e32 vcc, s1, v112
	s_and_saveexec_b64 s[70:71], s[4:5]
	s_xor_b64 s[70:71], exec, s[70:71]
	s_ashr_i32 s55, s54, 31
	s_or_saveexec_b64 s[70:71], s[70:71]
	v_mul_f32_e32 v113, 0x4b800000, v112
	v_cndmask_b32_e32 v112, v112, v113, vcc
	v_rsq_f32_e32 v112, v112
	v_mov_b64_e32 v[114:115], s[54:55]
	v_mul_f32_e32 v113, 0x45800000, v112
	v_cndmask_b32_e32 v112, v112, v113, vcc
	s_xor_b64 exec, exec, s[70:71]
	s_cbranch_execz .LBB0_324
	v_div_scale_f32 v113, s[72:73], v112, v112, 1.0
	v_rcp_f32_e32 v114, v113
	v_div_scale_f32 v115, vcc, 1.0, v112, 1.0
	s_ashr_i32 s55, s54, 31
	v_fma_f32 v116, -v113, v114, 1.0
	v_fmac_f32_e32 v114, v116, v114
	v_mul_f32_e32 v116, v115, v114
	v_fma_f32 v117, -v113, v116, v115
	v_fmac_f32_e32 v116, v117, v114
	v_fma_f32 v113, -v113, v116, v115
	s_lshl_b64 s[72:73], s[54:55], 2
	v_div_fmas_f32 v113, v113, v114, v116
	s_add_u32 s72, s39, s72
	v_div_fixup_f32 v113, v113, v112, 1.0
	s_addc_u32 s73, s65, s73
	v_mov_b64_e32 v[114:115], s[54:55]
	global_store_dword v129, v113, s[72:73]

.LBB0_325:
	v_pk_mul_f32 v[112:113], v[78:79], v[78:79]
	v_pk_mul_f32 v[114:115], v[76:77], v[76:77]
	s_nop 0
	v_pk_mov_b32 v[116:117], v[114:115], v[112:113] op_sel:[1,0]
	v_mov_b32_e32 v115, v113
	v_pk_add_f32 v[112:113], v[116:117], v[114:115]
	v_pk_mul_f32 v[114:115], v[74:75], v[74:75]
	v_pk_add_f32 v[112:113], v[112:113], v[112:113] op_sel_hi:[0,1]
	v_pk_mul_f32 v[116:117], v[72:73], v[72:73]
	v_mul_f32_e32 v112, v68, v68
	v_pk_mov_b32 v[118:119], v[116:117], v[114:115] op_sel:[1,0]
	v_mov_b32_e32 v117, v115
	v_pk_add_f32 v[114:115], v[118:119], v[116:117]
	v_pk_fma_f32 v[116:117], v[68:69], v[68:69], v[112:113] op_sel_hi:[1,1,0]
	v_mul_f32_e32 v112, v70, v70
	v_pk_add_f32 v[114:115], v[114:115], v[114:115] op_sel_hi:[0,1]
	v_pk_fma_f32 v[118:119], v[70:71], v[70:71], v[112:113] op_sel_hi:[1,1,0]
	v_mul_f32_e32 v116, v64, v64
	v_mul_f32_e32 v118, v65, v65
	v_mul_f32_e32 v114, v66, v66
	v_mul_f32_e32 v112, v67, v67
	v_pk_add_f32 v[116:117], v[116:117], v[118:119]
	v_pk_add_f32 v[112:113], v[114:115], v[112:113]
	s_nop 0
	v_pk_add_f32 v[112:113], v[116:117], v[112:113]
	s_nop 0
	v_add_f32_e32 v112, v112, v113
	s_waitcnt lgkmcnt(0)
	s_nop 1
	v_add_f32_dpp v112, v112, v112 quad_perm:[1,0,3,2] row_mask:0xf bank_mask:0xf
	s_waitcnt lgkmcnt(0)
	s_nop 1
	v_add_f32_dpp v112, v112, v112 quad_perm:[2,3,0,1] row_mask:0xf bank_mask:0xf
	s_waitcnt lgkmcnt(0)
	s_nop 1
	v_add_f32_dpp v112, v112, v112 row_half_mirror row_mask:0xf bank_mask:0xf
	s_waitcnt lgkmcnt(0)
	s_nop 1
	v_add_f32_dpp v112, v112, v112 row_mirror row_mask:0xf bank_mask:0xf
	s_waitcnt lgkmcnt(0)
	v_mov_b32_e32 v113, v112
	s_nop 1
	v_permlane16_swap_b32_e32 v112, v113
	v_add_f32_e32 v112, v112, v113
	s_waitcnt lgkmcnt(0)
	v_mov_b32_e32 v113, v112
	s_nop 1
	v_permlane32_swap_b32_e32 v112, v113
	v_add_f32_e32 v112, v112, v113
	v_fmamk_f32 v112, v112, 0x3a800000, v144
	v_cmp_gt_f32_e32 vcc, s1, v112
	s_and_saveexec_b64 s[48:49], s[4:5]
	s_xor_b64 s[48:49], exec, s[48:49]
	s_ashr_i32 s47, s46, 31
	s_or_saveexec_b64 s[48:49], s[48:49]
	v_mul_f32_e32 v113, 0x4b800000, v112
	v_cndmask_b32_e32 v112, v112, v113, vcc
	v_rsq_f32_e32 v112, v112
	v_mov_b64_e32 v[114:115], s[46:47]
	v_mul_f32_e32 v113, 0x45800000, v112
	v_cndmask_b32_e32 v112, v112, v113, vcc
	s_xor_b64 exec, exec, s[48:49]
	s_cbranch_execz .LBB0_329
	v_div_scale_f32 v113, s[54:55], v112, v112, 1.0
	v_rcp_f32_e32 v114, v113
	v_div_scale_f32 v115, vcc, 1.0, v112, 1.0
	s_ashr_i32 s47, s46, 31
	v_fma_f32 v116, -v113, v114, 1.0
	v_fmac_f32_e32 v114, v116, v114
	v_mul_f32_e32 v116, v115, v114
	v_fma_f32 v117, -v113, v116, v115
	v_fmac_f32_e32 v116, v117, v114
	v_fma_f32 v113, -v113, v116, v115
	s_lshl_b64 s[54:55], s[46:47], 2
	v_div_fmas_f32 v113, v113, v114, v116
	s_add_u32 s54, s39, s54
	v_div_fixup_f32 v113, v113, v112, 1.0
	s_addc_u32 s55, s65, s55
	v_mov_b64_e32 v[114:115], s[46:47]
	global_store_dword v129, v113, s[54:55]

.LBB0_330:
	v_pk_mul_f32 v[112:113], v[62:63], v[62:63]
	v_pk_mul_f32 v[114:115], v[60:61], v[60:61]
	s_nop 0
	v_pk_mov_b32 v[116:117], v[114:115], v[112:113] op_sel:[1,0]
	v_mov_b32_e32 v115, v113
	v_pk_add_f32 v[112:113], v[116:117], v[114:115]
	v_pk_mul_f32 v[114:115], v[58:59], v[58:59]
	v_pk_add_f32 v[112:113], v[112:113], v[112:113] op_sel_hi:[0,1]
	v_pk_mul_f32 v[116:117], v[56:57], v[56:57]
	v_mul_f32_e32 v112, v52, v52
	v_pk_mov_b32 v[118:119], v[116:117], v[114:115] op_sel:[1,0]
	v_mov_b32_e32 v117, v115
	v_pk_add_f32 v[114:115], v[118:119], v[116:117]
	v_pk_fma_f32 v[116:117], v[52:53], v[52:53], v[112:113] op_sel_hi:[1,1,0]
	v_mul_f32_e32 v112, v54, v54
	v_pk_add_f32 v[114:115], v[114:115], v[114:115] op_sel_hi:[0,1]
	v_pk_fma_f32 v[118:119], v[54:55], v[54:55], v[112:113] op_sel_hi:[1,1,0]
	v_mul_f32_e32 v116, v48, v48
	v_mul_f32_e32 v118, v49, v49
	v_mul_f32_e32 v114, v50, v50
	v_mul_f32_e32 v112, v51, v51
	v_pk_add_f32 v[116:117], v[116:117], v[118:119]
	v_pk_add_f32 v[112:113], v[114:115], v[112:113]
	s_nop 0
	v_pk_add_f32 v[112:113], v[116:117], v[112:113]
	s_nop 0
	v_add_f32_e32 v112, v112, v113
	s_waitcnt lgkmcnt(0)
	s_nop 1
	v_add_f32_dpp v112, v112, v112 quad_perm:[1,0,3,2] row_mask:0xf bank_mask:0xf
	s_waitcnt lgkmcnt(0)
	s_nop 1
	v_add_f32_dpp v112, v112, v112 quad_perm:[2,3,0,1] row_mask:0xf bank_mask:0xf
	s_waitcnt lgkmcnt(0)
	s_nop 1
	v_add_f32_dpp v112, v112, v112 row_half_mirror row_mask:0xf bank_mask:0xf
	s_waitcnt lgkmcnt(0)
	s_nop 1
	v_add_f32_dpp v112, v112, v112 row_mirror row_mask:0xf bank_mask:0xf
	s_waitcnt lgkmcnt(0)
	v_mov_b32_e32 v113, v112
	s_nop 1
	v_permlane16_swap_b32_e32 v112, v113
	v_add_f32_e32 v112, v112, v113
	s_waitcnt lgkmcnt(0)
	v_mov_b32_e32 v113, v112
	s_nop 1
	v_permlane32_swap_b32_e32 v112, v113
	v_add_f32_e32 v112, v112, v113
	v_fmamk_f32 v112, v112, 0x3a800000, v144
	v_cmp_gt_f32_e32 vcc, s1, v112
	s_and_saveexec_b64 s[44:45], s[4:5]
	s_xor_b64 s[44:45], exec, s[44:45]
	s_ashr_i32 s43, s42, 31
	s_or_saveexec_b64 s[44:45], s[44:45]
	v_mul_f32_e32 v113, 0x4b800000, v112
	v_cndmask_b32_e32 v112, v112, v113, vcc
	v_rsq_f32_e32 v112, v112
	v_mov_b64_e32 v[114:115], s[42:43]
	v_mul_f32_e32 v113, 0x45800000, v112
	v_cndmask_b32_e32 v112, v112, v113, vcc
	s_xor_b64 exec, exec, s[44:45]
	s_cbranch_execz .LBB0_334
	v_div_scale_f32 v113, s[46:47], v112, v112, 1.0
	v_rcp_f32_e32 v114, v113
	v_div_scale_f32 v115, vcc, 1.0, v112, 1.0
	s_ashr_i32 s43, s42, 31
	v_fma_f32 v116, -v113, v114, 1.0
	v_fmac_f32_e32 v114, v116, v114
	v_mul_f32_e32 v116, v115, v114
	v_fma_f32 v117, -v113, v116, v115
	v_fmac_f32_e32 v116, v117, v114
	v_fma_f32 v113, -v113, v116, v115
	s_lshl_b64 s[46:47], s[42:43], 2
	v_div_fmas_f32 v113, v113, v114, v116
	s_add_u32 s46, s39, s46
	v_div_fixup_f32 v113, v113, v112, 1.0
	s_addc_u32 s47, s65, s47
	v_mov_b64_e32 v[114:115], s[42:43]
	global_store_dword v129, v113, s[46:47]

.LBB0_335:
	v_pk_mul_f32 v[112:113], v[46:47], v[46:47]
	v_pk_mul_f32 v[114:115], v[44:45], v[44:45]
	s_nop 0
	v_pk_mov_b32 v[116:117], v[114:115], v[112:113] op_sel:[1,0]
	v_mov_b32_e32 v115, v113
	v_pk_add_f32 v[112:113], v[116:117], v[114:115]
	v_pk_mul_f32 v[114:115], v[42:43], v[42:43]
	v_pk_add_f32 v[112:113], v[112:113], v[112:113] op_sel_hi:[0,1]
	v_pk_mul_f32 v[116:117], v[40:41], v[40:41]
	v_mul_f32_e32 v112, v36, v36
	v_pk_mov_b32 v[118:119], v[116:117], v[114:115] op_sel:[1,0]
	v_mov_b32_e32 v117, v115
	v_pk_add_f32 v[114:115], v[118:119], v[116:117]
	v_pk_fma_f32 v[116:117], v[36:37], v[36:37], v[112:113] op_sel_hi:[1,1,0]
	v_mul_f32_e32 v112, v38, v38
	v_pk_add_f32 v[114:115], v[114:115], v[114:115] op_sel_hi:[0,1]
	v_pk_fma_f32 v[118:119], v[38:39], v[38:39], v[112:113] op_sel_hi:[1,1,0]
	v_mul_f32_e32 v116, v32, v32
	v_mul_f32_e32 v118, v33, v33
	v_mul_f32_e32 v114, v34, v34
	v_mul_f32_e32 v112, v35, v35
	v_pk_add_f32 v[116:117], v[116:117], v[118:119]
	v_pk_add_f32 v[112:113], v[114:115], v[112:113]
	s_nop 0
	v_pk_add_f32 v[112:113], v[116:117], v[112:113]
	s_nop 0
	v_add_f32_e32 v112, v112, v113
	s_waitcnt lgkmcnt(0)
	s_nop 1
	v_add_f32_dpp v112, v112, v112 quad_perm:[1,0,3,2] row_mask:0xf bank_mask:0xf
	s_waitcnt lgkmcnt(0)
	s_nop 1
	v_add_f32_dpp v112, v112, v112 quad_perm:[2,3,0,1] row_mask:0xf bank_mask:0xf
	s_waitcnt lgkmcnt(0)
	s_nop 1
	v_add_f32_dpp v112, v112, v112 row_half_mirror row_mask:0xf bank_mask:0xf
	s_waitcnt lgkmcnt(0)
	s_nop 1
	v_add_f32_dpp v112, v112, v112 row_mirror row_mask:0xf bank_mask:0xf
	s_waitcnt lgkmcnt(0)
	v_mov_b32_e32 v113, v112
	s_nop 1
	v_permlane16_swap_b32_e32 v112, v113
	v_add_f32_e32 v112, v112, v113
	s_waitcnt lgkmcnt(0)
	v_mov_b32_e32 v113, v112
	s_nop 1
	v_permlane32_swap_b32_e32 v112, v113
	v_add_f32_e32 v112, v112, v113
	v_fmamk_f32 v112, v112, 0x3a800000, v144
	v_cmp_gt_f32_e32 vcc, s1, v112
	s_and_saveexec_b64 s[36:37], s[4:5]
	s_xor_b64 s[36:37], exec, s[36:37]
	s_ashr_i32 s35, s34, 31
	s_or_saveexec_b64 s[36:37], s[36:37]
	v_mul_f32_e32 v113, 0x4b800000, v112
	v_cndmask_b32_e32 v112, v112, v113, vcc
	v_rsq_f32_e32 v112, v112
	v_mov_b64_e32 v[114:115], s[34:35]
	v_mul_f32_e32 v113, 0x45800000, v112
	v_cndmask_b32_e32 v112, v112, v113, vcc
	s_xor_b64 exec, exec, s[36:37]
	s_cbranch_execz .LBB0_339
	v_div_scale_f32 v113, s[42:43], v112, v112, 1.0
	v_rcp_f32_e32 v114, v113
	v_div_scale_f32 v115, vcc, 1.0, v112, 1.0
	s_ashr_i32 s35, s34, 31
	v_fma_f32 v116, -v113, v114, 1.0
	v_fmac_f32_e32 v114, v116, v114
	v_mul_f32_e32 v116, v115, v114
	v_fma_f32 v117, -v113, v116, v115
	v_fmac_f32_e32 v116, v117, v114
	v_fma_f32 v113, -v113, v116, v115
	s_lshl_b64 s[42:43], s[34:35], 2
	v_div_fmas_f32 v113, v113, v114, v116
	s_add_u32 s42, s39, s42
	v_div_fixup_f32 v113, v113, v112, 1.0
	s_addc_u32 s43, s65, s43
	v_mov_b64_e32 v[114:115], s[34:35]
	global_store_dword v129, v113, s[42:43]

.LBB0_340:
	v_pk_mul_f32 v[112:113], v[30:31], v[30:31]
	v_pk_mul_f32 v[114:115], v[28:29], v[28:29]
	s_nop 0
	v_pk_mov_b32 v[116:117], v[114:115], v[112:113] op_sel:[1,0]
	v_mov_b32_e32 v115, v113
	v_pk_add_f32 v[112:113], v[116:117], v[114:115]
	v_pk_mul_f32 v[114:115], v[26:27], v[26:27]
	v_pk_add_f32 v[112:113], v[112:113], v[112:113] op_sel_hi:[0,1]
	v_pk_mul_f32 v[116:117], v[24:25], v[24:25]
	v_mul_f32_e32 v112, v20, v20
	v_pk_mov_b32 v[118:119], v[116:117], v[114:115] op_sel:[1,0]
	v_mov_b32_e32 v117, v115
	v_pk_add_f32 v[114:115], v[118:119], v[116:117]
	v_pk_fma_f32 v[116:117], v[20:21], v[20:21], v[112:113] op_sel_hi:[1,1,0]
	v_mul_f32_e32 v112, v22, v22
	v_pk_add_f32 v[114:115], v[114:115], v[114:115] op_sel_hi:[0,1]
	v_pk_fma_f32 v[118:119], v[22:23], v[22:23], v[112:113] op_sel_hi:[1,1,0]
	v_mul_f32_e32 v116, v16, v16
	v_mul_f32_e32 v118, v17, v17
	v_mul_f32_e32 v114, v18, v18
	v_mul_f32_e32 v112, v19, v19
	v_pk_add_f32 v[116:117], v[116:117], v[118:119]
	v_pk_add_f32 v[112:113], v[114:115], v[112:113]
	s_nop 0
	v_pk_add_f32 v[112:113], v[116:117], v[112:113]
	s_nop 0
	v_add_f32_e32 v112, v112, v113
	s_waitcnt lgkmcnt(0)
	s_nop 1
	v_add_f32_dpp v112, v112, v112 quad_perm:[1,0,3,2] row_mask:0xf bank_mask:0xf
	s_waitcnt lgkmcnt(0)
	s_nop 1
	v_add_f32_dpp v112, v112, v112 quad_perm:[2,3,0,1] row_mask:0xf bank_mask:0xf
	s_waitcnt lgkmcnt(0)
	s_nop 1
	v_add_f32_dpp v112, v112, v112 row_half_mirror row_mask:0xf bank_mask:0xf
	s_waitcnt lgkmcnt(0)
	s_nop 1
	v_add_f32_dpp v112, v112, v112 row_mirror row_mask:0xf bank_mask:0xf
	s_waitcnt lgkmcnt(0)
	v_mov_b32_e32 v113, v112
	s_nop 1
	v_permlane16_swap_b32_e32 v112, v113
	v_add_f32_e32 v112, v112, v113
	s_waitcnt lgkmcnt(0)
	v_mov_b32_e32 v113, v112
	s_nop 1
	v_permlane32_swap_b32_e32 v112, v113
	v_add_f32_e32 v112, v112, v113
	v_fmamk_f32 v112, v112, 0x3a800000, v144
	v_cmp_gt_f32_e32 vcc, s1, v112
	s_and_saveexec_b64 s[30:31], s[4:5]
	s_xor_b64 s[30:31], exec, s[30:31]
	s_ashr_i32 s29, s28, 31
	s_or_saveexec_b64 s[30:31], s[30:31]
	v_mul_f32_e32 v113, 0x4b800000, v112
	v_cndmask_b32_e32 v112, v112, v113, vcc
	v_rsq_f32_e32 v112, v112
	v_mov_b64_e32 v[114:115], s[28:29]
	v_mul_f32_e32 v113, 0x45800000, v112
	v_cndmask_b32_e32 v112, v112, v113, vcc
	s_xor_b64 exec, exec, s[30:31]
	s_cbranch_execz .LBB0_344
	v_div_scale_f32 v113, s[34:35], v112, v112, 1.0
	v_rcp_f32_e32 v114, v113
	v_div_scale_f32 v115, vcc, 1.0, v112, 1.0
	s_ashr_i32 s29, s28, 31
	v_fma_f32 v116, -v113, v114, 1.0
	v_fmac_f32_e32 v114, v116, v114
	v_mul_f32_e32 v116, v115, v114
	v_fma_f32 v117, -v113, v116, v115
	v_fmac_f32_e32 v116, v117, v114
	v_fma_f32 v113, -v113, v116, v115
	s_lshl_b64 s[34:35], s[28:29], 2
	v_div_fmas_f32 v113, v113, v114, v116
	s_add_u32 s34, s39, s34
	v_div_fixup_f32 v113, v113, v112, 1.0
	s_addc_u32 s35, s65, s35
	v_mov_b64_e32 v[114:115], s[28:29]
	global_store_dword v129, v113, s[34:35]

.LBB0_345:
	v_pk_mul_f32 v[112:113], v[14:15], v[14:15]
	v_pk_mul_f32 v[114:115], v[12:13], v[12:13]
	s_nop 0
	v_pk_mov_b32 v[116:117], v[114:115], v[112:113] op_sel:[1,0]
	v_mov_b32_e32 v115, v113
	v_pk_add_f32 v[112:113], v[116:117], v[114:115]
	v_pk_mul_f32 v[114:115], v[10:11], v[10:11]
	v_pk_add_f32 v[112:113], v[112:113], v[112:113] op_sel_hi:[0,1]
	v_pk_mul_f32 v[116:117], v[8:9], v[8:9]
	v_mul_f32_e32 v112, v4, v4
	v_pk_mov_b32 v[118:119], v[116:117], v[114:115] op_sel:[1,0]
	v_mov_b32_e32 v117, v115
	v_pk_add_f32 v[114:115], v[118:119], v[116:117]
	v_pk_fma_f32 v[116:117], v[4:5], v[4:5], v[112:113] op_sel_hi:[1,1,0]
	v_mul_f32_e32 v112, v6, v6
	v_pk_add_f32 v[114:115], v[114:115], v[114:115] op_sel_hi:[0,1]
	v_pk_fma_f32 v[118:119], v[6:7], v[6:7], v[112:113] op_sel_hi:[1,1,0]
	v_mul_f32_e32 v116, v0, v0
	v_mul_f32_e32 v118, v1, v1
	v_mul_f32_e32 v114, v2, v2
	v_mul_f32_e32 v112, v3, v3
	v_pk_add_f32 v[116:117], v[116:117], v[118:119]
	v_pk_add_f32 v[112:113], v[114:115], v[112:113]
	s_nop 0
	v_pk_add_f32 v[112:113], v[116:117], v[112:113]
	s_nop 0
	v_add_f32_e32 v112, v112, v113
	s_waitcnt lgkmcnt(0)
	s_nop 1
	v_add_f32_dpp v112, v112, v112 quad_perm:[1,0,3,2] row_mask:0xf bank_mask:0xf
	s_waitcnt lgkmcnt(0)
	s_nop 1
	v_add_f32_dpp v112, v112, v112 quad_perm:[2,3,0,1] row_mask:0xf bank_mask:0xf
	s_waitcnt lgkmcnt(0)
	s_nop 1
	v_add_f32_dpp v112, v112, v112 row_half_mirror row_mask:0xf bank_mask:0xf
	s_waitcnt lgkmcnt(0)
	s_nop 1
	v_add_f32_dpp v112, v112, v112 row_mirror row_mask:0xf bank_mask:0xf
	s_waitcnt lgkmcnt(0)
	v_mov_b32_e32 v113, v112
	s_nop 1
	v_permlane16_swap_b32_e32 v112, v113
	v_add_f32_e32 v112, v112, v113
	s_waitcnt lgkmcnt(0)
	v_mov_b32_e32 v113, v112
	s_nop 1
	v_permlane32_swap_b32_e32 v112, v113
	v_add_f32_e32 v112, v112, v113
	v_fmamk_f32 v112, v112, 0x3a800000, v144
	v_cmp_gt_f32_e32 vcc, s1, v112
	s_and_saveexec_b64 s[26:27], s[4:5]
	s_xor_b64 s[26:27], exec, s[26:27]
	s_ashr_i32 s23, s22, 31
	s_or_saveexec_b64 s[26:27], s[26:27]
	v_mul_f32_e32 v113, 0x4b800000, v112
	v_cndmask_b32_e32 v112, v112, v113, vcc
	v_rsq_f32_e32 v112, v112
	v_mov_b64_e32 v[114:115], s[22:23]
	v_mul_f32_e32 v113, 0x45800000, v112
	v_cndmask_b32_e32 v112, v112, v113, vcc
	s_xor_b64 exec, exec, s[26:27]
	s_cbranch_execz .LBB0_290
	v_div_scale_f32 v113, s[28:29], v112, v112, 1.0
	v_rcp_f32_e32 v114, v113
	v_div_scale_f32 v115, vcc, 1.0, v112, 1.0
	s_ashr_i32 s23, s22, 31
	v_fma_f32 v116, -v113, v114, 1.0
	v_fmac_f32_e32 v114, v116, v114
	v_mul_f32_e32 v116, v115, v114
	v_fma_f32 v117, -v113, v116, v115
	v_fmac_f32_e32 v116, v117, v114
	v_fma_f32 v113, -v113, v116, v115
	s_lshl_b64 s[28:29], s[22:23], 2
	v_div_fmas_f32 v113, v113, v114, v116
	s_add_u32 s28, s39, s28
	v_div_fixup_f32 v113, v113, v112, 1.0
	s_addc_u32 s29, s65, s29
	v_mov_b64_e32 v[114:115], s[22:23]
	global_store_dword v129, v113, s[28:29]
	s_branch .LBB0_290

.LBB0_582:
	s_waitcnt vmcnt(0)
	v_lshlrev_b32_e32 v144, 16, v134
	v_and_b32_e32 v145, 0xffff0000, v134
	v_lshlrev_b32_e32 v134, 16, v135
	v_and_b32_e32 v135, 0xffff0000, v135
	v_lshlrev_b32_e32 v147, 16, v133
	v_lshlrev_b32_e32 v146, 16, v132
	v_and_b32_e32 v133, 0xffff0000, v133
	v_and_b32_e32 v132, 0xffff0000, v132
	v_lshlrev_b32_e32 v151, 16, v128
	v_and_b32_e32 v153, 0xffff0000, v128
	v_mul_f32_e32 v128, v135, v135
	v_mul_f32_e32 v150, v145, v145
	v_lshlrev_b32_e32 v154, 16, v129
	v_and_b32_e32 v155, 0xffff0000, v129
	v_pk_fma_f32 v[128:129], v[134:135], v[134:135], v[128:129] op_sel_hi:[1,1,0]
	v_pk_mul_f32 v[156:157], v[132:133], v[132:133]
	v_pk_fma_f32 v[158:159], v[144:145], v[144:145], v[150:151] op_sel_hi:[1,1,0]
	v_pk_fma_f32 v[156:157], v[146:147], v[146:147], v[156:157]
	v_mov_b32_e32 v150, v158
	v_mov_b32_e32 v160, v128
	v_mov_b32_e32 v161, v151
	v_and_b32_e32 v149, 0xffff0000, v130
	v_mul_f32_e32 v143, v153, v153
	v_pk_add_f32 v[128:129], v[158:159], v[128:129]
	v_pk_mul_f32 v[158:159], v[150:151], v[160:161]
	v_pk_add_f32 v[156:157], v[156:157], v[156:157] op_sel:[0,1] op_sel_hi:[1,0]
	v_lshlrev_b32_e32 v148, 16, v130
	v_lshlrev_b32_e32 v130, 16, v131
	v_and_b32_e32 v131, 0xffff0000, v131
	v_mov_b32_e32 v129, v159
	v_mov_b32_e32 v157, v143
	v_mul_f32_e32 v150, v149, v149
	v_pk_add_f32 v[128:129], v[128:129], v[156:157]
	v_pk_fma_f32 v[156:157], v[148:149], v[148:149], v[150:151] op_sel_hi:[1,1,0]
	v_mul_f32_e32 v150, v131, v131
	v_mul_f32_e32 v152, v154, v154
	v_mul_f32_e32 v162, v155, v155
	v_pk_fma_f32 v[158:159], v[130:131], v[130:131], v[150:151] op_sel_hi:[1,1,0]
	v_mov_b32_e32 v157, v152
	v_mov_b32_e32 v159, v162
	v_pk_add_f32 v[156:157], v[156:157], v[158:159]
	v_lshlrev_b32_e32 v158, 16, v122
	v_pk_add_f32 v[128:129], v[128:129], v[156:157]
	v_and_b32_e32 v159, 0xffff0000, v122
	v_add_f32_e32 v128, v128, v129
	v_lshlrev_b32_e32 v160, 16, v123
	v_and_b32_e32 v161, 0xffff0000, v123
	v_lshlrev_b32_e32 v162, 16, v120
	v_and_b32_e32 v163, 0xffff0000, v120
	s_waitcnt lgkmcnt(0)
	s_nop 1
	v_add_f32_dpp v128, v128, v128 quad_perm:[1,0,3,2] row_mask:0xf bank_mask:0xf
	v_lshlrev_b32_e32 v164, 16, v121
	v_and_b32_e32 v165, 0xffff0000, v121
	v_lshlrev_b32_e32 v156, 16, v124
	v_and_b32_e32 v157, 0xffff0000, v124
	s_waitcnt lgkmcnt(0)
	s_nop 1
	v_add_f32_dpp v129, v128, v128 quad_perm:[2,3,0,1] row_mask:0xf bank_mask:0xf
	v_lshlrev_b32_e32 v128, 16, v126
	v_lshlrev_b32_e32 v124, 16, v125
	v_and_b32_e32 v125, 0xffff0000, v125
	v_mov_b32_e32 v152, v151
	s_waitcnt lgkmcnt(0)
	s_nop 1
	v_add_f32_dpp v143, v129, v129 row_half_mirror row_mask:0xf bank_mask:0xf
	v_and_b32_e32 v129, 0xffff0000, v126
	v_lshlrev_b32_e32 v126, 16, v127
	v_and_b32_e32 v127, 0xffff0000, v127
	s_waitcnt lgkmcnt(0)
	s_nop 1
	v_add_f32_dpp v143, v143, v143 row_mirror row_mask:0xf bank_mask:0xf
	s_waitcnt lgkmcnt(0)
	v_mov_b32_e32 v150, v143
	s_nop 1
	v_permlane16_swap_b32_e32 v143, v150
	v_add_f32_e32 v143, v143, v150
	s_waitcnt lgkmcnt(0)
	v_mov_b32_e32 v122, v143
	v_mov_b32_e32 v150, v143
	s_nop 1
	v_permlane32_swap_b32_e32 v122, v150
	v_add_f32_e32 v122, v122, v150
	v_fmamk_f32 v122, v122, 0x3a800000, v142
	v_mul_f32_e32 v123, 0x4b800000, v122
	v_cmp_gt_f32_e32 vcc, s7, v122
	s_nop 1
	v_cndmask_b32_e32 v122, v122, v123, vcc
	v_rsq_f32_e32 v122, v122
	s_nop 0
	v_mul_f32_e32 v120, 0x45800000, v122
	v_cndmask_b32_e32 v150, v122, v120, vcc
	v_pk_mul_f32 v[120:121], v[150:151], v[134:135] op_sel_hi:[0,1]
	v_pk_mul_f32 v[122:123], v[150:151], v[144:145] op_sel_hi:[0,1]
	v_pk_mul_f32 v[122:123], v[0:1], v[122:123]
	v_pk_mul_f32 v[120:121], v[2:3], v[120:121]
	v_pk_fma_f32 v[122:123], v[64:65], v[128:129], v[122:123] op_sel_hi:[0,1,1]
	v_pk_fma_f32 v[120:121], v[64:65], v[126:127], v[120:121] op_sel_hi:[0,1,1]
	v_pk_mul_f32 v[126:127], v[120:121], v[120:121]
	v_pk_mul_f32 v[128:129], v[122:123], v[122:123]
	s_nop 0
	v_pk_mov_b32 v[134:135], v[128:129], v[126:127] op_sel:[1,0]
	v_mov_b32_e32 v129, v127
	v_pk_add_f32 v[126:127], v[134:135], v[128:129]
	s_nop 0
	v_pk_add_f32 v[144:145], v[126:127], v[126:127] op_sel_hi:[0,1]
	v_mov_b32_e32 v126, v147
	v_mov_b32_e32 v127, v133
	v_mov_b32_e32 v147, v132
	v_pk_mul_f32 v[126:127], v[150:151], v[126:127] op_sel_hi:[0,1]
	v_pk_mul_f32 v[128:129], v[150:151], v[146:147] op_sel_hi:[0,1]
	v_pk_mul_f32 v[128:129], v[4:5], v[128:129]
	v_pk_mul_f32 v[126:127], v[6:7], v[126:127]
	s_nop 0
	v_pk_fma_f32 v[124:125], v[64:65], v[124:125], v[126:127] op_sel_hi:[0,1,1]
	v_pk_fma_f32 v[126:127], v[64:65], v[156:157], v[128:129] op_sel_hi:[0,1,1]
	v_pk_mul_f32 v[128:129], v[124:125], v[124:125]
	v_pk_mul_f32 v[132:133], v[126:127], v[126:127]
	s_nop 0
	v_pk_mov_b32 v[134:135], v[132:133], v[128:129] op_sel:[1,0]
	v_mov_b32_e32 v133, v129
	v_pk_add_f32 v[128:129], v[134:135], v[132:133]
	v_pk_mul_f32 v[134:135], v[150:151], v[152:153] op_sel_hi:[0,1]
	v_pk_add_f32 v[146:147], v[128:129], v[128:129] op_sel_hi:[0,1]
	v_pk_mul_f32 v[128:129], v[150:151], v[130:131] op_sel_hi:[0,1]
	v_pk_mul_f32 v[130:131], v[150:151], v[148:149] op_sel_hi:[0,1]
	v_pk_mul_f32 v[130:131], v[8:9], v[130:131]
	v_pk_mul_f32 v[128:129], v[10:11], v[128:129]
	v_pk_fma_f32 v[130:131], v[64:65], v[158:159], v[130:131] op_sel_hi:[0,1,1]
	v_pk_fma_f32 v[128:129], v[64:65], v[160:161], v[128:129] op_sel_hi:[0,1,1]
	v_mul_f32_e32 v132, v130, v130
	v_pk_fma_f32 v[148:149], v[130:131], v[130:131], v[132:133] op_sel_hi:[1,1,0]
	v_mul_f32_e32 v132, v128, v128
	v_pk_fma_f32 v[156:157], v[128:129], v[128:129], v[132:133] op_sel_hi:[1,1,0]
	v_pk_mul_f32 v[132:133], v[150:151], v[154:155] op_sel_hi:[0,1]
	v_pk_mul_f32 v[134:135], v[12:13], v[134:135]
	v_pk_mul_f32 v[132:133], v[14:15], v[132:133]
	v_pk_fma_f32 v[134:135], v[64:65], v[162:163], v[134:135] op_sel_hi:[0,1,1]
	v_pk_fma_f32 v[132:133], v[64:65], v[164:165], v[132:133] op_sel_hi:[0,1,1]
	v_mul_f32_e32 v148, v134, v134
	v_mul_f32_e32 v156, v135, v135
	v_mul_f32_e32 v144, v132, v132
	v_mul_f32_e32 v146, v133, v133
	v_pk_add_f32 v[148:149], v[148:149], v[156:157]
	v_pk_add_f32 v[144:145], v[144:145], v[146:147]
	s_nop 0
	v_pk_add_f32 v[144:145], v[148:149], v[144:145]
	s_nop 0
	v_add_f32_e32 v64, v144, v145
	s_waitcnt lgkmcnt(0)
	s_nop 1
	v_add_f32_dpp v64, v64, v64 quad_perm:[1,0,3,2] row_mask:0xf bank_mask:0xf
	s_waitcnt lgkmcnt(0)
	s_nop 1
	v_add_f32_dpp v64, v64, v64 quad_perm:[2,3,0,1] row_mask:0xf bank_mask:0xf
	s_waitcnt lgkmcnt(0)
	s_nop 1
	v_add_f32_dpp v64, v64, v64 row_half_mirror row_mask:0xf bank_mask:0xf
	s_waitcnt lgkmcnt(0)
	s_nop 1
	v_add_f32_dpp v64, v64, v64 row_mirror row_mask:0xf bank_mask:0xf
	s_waitcnt lgkmcnt(0)
	v_mov_b32_e32 v143, v64
	s_nop 1
	v_permlane16_swap_b32_e32 v64, v143
	v_add_f32_e32 v64, v64, v143
	s_waitcnt lgkmcnt(0)
	v_mov_b32_e32 v143, v64
	s_nop 1
	v_permlane32_swap_b32_e32 v64, v143
	v_add_f32_e32 v64, v64, v143
	v_fmamk_f32 v64, v64, 0x3a800000, v142
	v_mul_f32_e32 v143, 0x4b800000, v64
	v_cmp_gt_f32_e32 vcc, s7, v64
	s_nop 1
	v_cndmask_b32_e32 v64, v64, v143, vcc
	v_rsq_f32_e32 v64, v64
	s_nop 0
	v_mul_f32_e32 v143, 0x45800000, v64
	v_cndmask_b32_e32 v64, v64, v143, vcc
	s_and_saveexec_b64 s[26:27], s[2:3]
	s_cbranch_execz .LBB0_584
	v_div_scale_f32 v143, s[36:37], v64, v64, 1.0
	v_rcp_f32_e32 v144, v143
	v_div_scale_f32 v145, vcc, 1.0, v64, 1.0
	s_add_u32 s24, s30, s24
	v_fma_f32 v146, -v143, v144, 1.0
	v_fmac_f32_e32 v144, v146, v144
	v_mul_f32_e32 v146, v145, v144
	v_fma_f32 v147, -v143, v146, v145
	v_fmac_f32_e32 v146, v147, v144
	v_fma_f32 v143, -v143, v146, v145
	v_div_fmas_f32 v143, v143, v144, v146
	v_div_fixup_f32 v143, v143, v64, 1.0
	s_addc_u32 s25, s31, s25
	global_store_dword v65, v143, s[24:25]

.LBB0_587:
	v_pk_mul_f32 v[120:121], v[104:105], v[104:105]
	v_pk_mul_f32 v[122:123], v[94:95], v[94:95]
	v_mul_f32_e32 v64, v90, v90
	v_pk_mov_b32 v[124:125], v[122:123], v[120:121] op_sel:[1,0]
	v_mov_b32_e32 v123, v121
	v_pk_add_f32 v[120:121], v[124:125], v[122:123]
	v_pk_mul_f32 v[122:123], v[110:111], v[110:111]
	v_pk_mul_f32 v[124:125], v[92:93], v[92:93]
	v_pk_add_f32 v[120:121], v[120:121], v[120:121] op_sel_hi:[0,1]
	v_pk_mov_b32 v[126:127], v[124:125], v[122:123] op_sel:[1,0]
	v_mov_b32_e32 v125, v123
	v_pk_add_f32 v[122:123], v[126:127], v[124:125]
	v_pk_fma_f32 v[124:125], v[90:91], v[90:91], v[64:65] op_sel_hi:[1,1,0]
	v_mul_f32_e32 v64, v114, v114
	v_pk_add_f32 v[122:123], v[122:123], v[122:123] op_sel_hi:[0,1]
	v_pk_fma_f32 v[126:127], v[114:115], v[114:115], v[64:65] op_sel_hi:[1,1,0]
	v_mul_f32_e32 v124, v88, v88
	v_mul_f32_e32 v126, v89, v89
	v_mul_f32_e32 v122, v118, v118
	v_mul_f32_e32 v120, v119, v119
	v_pk_add_f32 v[124:125], v[124:125], v[126:127]
	v_pk_add_f32 v[120:121], v[122:123], v[120:121]
	s_ashr_i32 s11, s10, 31
	v_pk_add_f32 v[120:121], v[124:125], v[120:121]
	s_nop 0
	v_add_f32_e32 v64, v120, v121
	s_waitcnt lgkmcnt(0)
	s_nop 1
	v_add_f32_dpp v64, v64, v64 quad_perm:[1,0,3,2] row_mask:0xf bank_mask:0xf
	s_waitcnt lgkmcnt(0)
	s_nop 1
	v_add_f32_dpp v64, v64, v64 quad_perm:[2,3,0,1] row_mask:0xf bank_mask:0xf
	s_waitcnt lgkmcnt(0)
	s_nop 1
	v_add_f32_dpp v64, v64, v64 row_half_mirror row_mask:0xf bank_mask:0xf
	s_waitcnt lgkmcnt(0)
	s_nop 1
	v_add_f32_dpp v64, v64, v64 row_mirror row_mask:0xf bank_mask:0xf
	s_waitcnt lgkmcnt(0)
	v_mov_b32_e32 v120, v64
	s_nop 1
	v_permlane16_swap_b32_e32 v64, v120
	v_add_f32_e32 v64, v64, v120
	s_waitcnt lgkmcnt(0)
	v_mov_b32_e32 v120, v64
	s_nop 1
	v_permlane32_swap_b32_e32 v64, v120
	v_add_f32_e32 v64, v64, v120
	v_fmamk_f32 v64, v64, 0x3a800000, v142
	v_mul_f32_e32 v120, 0x4b800000, v64
	v_cmp_gt_f32_e32 vcc, s7, v64
	s_nop 1
	v_cndmask_b32_e32 v64, v64, v120, vcc
	v_rsq_f32_e32 v64, v64
	s_nop 0
	v_mul_f32_e32 v120, 0x45800000, v64
	v_cndmask_b32_e32 v64, v64, v120, vcc
	v_pk_mul_f32 v[120:121], v[64:65], v[94:95] op_sel_hi:[0,1]
	v_pk_mul_f32 v[122:123], v[64:65], v[104:105] op_sel_hi:[0,1]
	v_pk_mul_f32 v[124:125], v[64:65], v[92:93] op_sel_hi:[0,1]
	v_pk_mul_f32 v[126:127], v[64:65], v[110:111] op_sel_hi:[0,1]
	v_pk_fma_f32 v[42:43], v[2:3], v[122:123], v[42:43]
	v_pk_fma_f32 v[40:41], v[0:1], v[120:121], v[40:41]
	v_pk_fma_f32 v[50:51], v[6:7], v[126:127], v[50:51]
	v_pk_fma_f32 v[48:49], v[4:5], v[124:125], v[48:49]
	v_pk_mul_f32 v[120:121], v[42:43], v[42:43]
	v_pk_mul_f32 v[122:123], v[40:41], v[40:41]
	v_pk_mul_f32 v[124:125], v[50:51], v[50:51]
	v_pk_mul_f32 v[126:127], v[48:49], v[48:49]
	v_pk_mov_b32 v[128:129], v[122:123], v[120:121] op_sel:[1,0]
	v_mov_b32_e32 v123, v121
	v_pk_add_f32 v[120:121], v[128:129], v[122:123]
	v_pk_mov_b32 v[122:123], v[126:127], v[124:125] op_sel:[1,0]
	v_mov_b32_e32 v127, v125
	v_pk_mul_f32 v[124:125], v[64:65], v[90:91] op_sel_hi:[0,1]
	v_pk_add_f32 v[120:121], v[120:121], v[120:121] op_sel_hi:[0,1]
	v_pk_add_f32 v[122:123], v[122:123], v[126:127]
	v_pk_mul_f32 v[126:127], v[64:65], v[114:115] op_sel_hi:[0,1]
	v_pk_fma_f32 v[56:57], v[8:9], v[124:125], v[56:57]
	v_pk_fma_f32 v[58:59], v[10:11], v[126:127], v[58:59]
	v_mul_f32_e32 v120, v56, v56
	v_pk_fma_f32 v[124:125], v[56:57], v[56:57], v[120:121] op_sel_hi:[1,1,0]
	v_mul_f32_e32 v120, v58, v58
	v_pk_mul_f32 v[128:129], v[64:65], v[88:89] op_sel_hi:[0,1]
	v_pk_mul_f32 v[130:131], v[64:65], v[118:119] op_sel_hi:[0,1]
	v_pk_add_f32 v[122:123], v[122:123], v[122:123] op_sel_hi:[0,1]
	v_pk_fma_f32 v[126:127], v[58:59], v[58:59], v[120:121] op_sel_hi:[1,1,0]
	v_pk_fma_f32 v[62:63], v[14:15], v[130:131], v[62:63]
	v_pk_fma_f32 v[60:61], v[12:13], v[128:129], v[60:61]
	v_mul_f32_e32 v120, v62, v62
	v_mul_f32_e32 v124, v60, v60
	v_mul_f32_e32 v126, v61, v61
	v_mul_f32_e32 v122, v63, v63
	v_pk_add_f32 v[124:125], v[124:125], v[126:127]
	v_pk_add_f32 v[120:121], v[120:121], v[122:123]
	s_nop 0
	v_pk_add_f32 v[120:121], v[124:125], v[120:121]
	s_nop 0
	v_add_f32_e32 v64, v120, v121
	s_waitcnt lgkmcnt(0)
	s_nop 1
	v_add_f32_dpp v64, v64, v64 quad_perm:[1,0,3,2] row_mask:0xf bank_mask:0xf
	s_waitcnt lgkmcnt(0)
	s_nop 1
	v_add_f32_dpp v64, v64, v64 quad_perm:[2,3,0,1] row_mask:0xf bank_mask:0xf
	s_waitcnt lgkmcnt(0)
	s_nop 1
	v_add_f32_dpp v64, v64, v64 row_half_mirror row_mask:0xf bank_mask:0xf
	s_waitcnt lgkmcnt(0)
	s_nop 1
	v_add_f32_dpp v64, v64, v64 row_mirror row_mask:0xf bank_mask:0xf
	s_waitcnt lgkmcnt(0)
	v_mov_b32_e32 v120, v64
	s_nop 1
	v_permlane16_swap_b32_e32 v64, v120
	v_add_f32_e32 v64, v64, v120
	s_waitcnt lgkmcnt(0)
	v_mov_b32_e32 v120, v64
	s_nop 1
	v_permlane32_swap_b32_e32 v64, v120
	v_add_f32_e32 v64, v64, v120
	v_fmamk_f32 v64, v64, 0x3a800000, v142
	v_mul_f32_e32 v120, 0x4b800000, v64
	v_cmp_gt_f32_e32 vcc, s7, v64
	s_nop 1
	v_cndmask_b32_e32 v64, v64, v120, vcc
	v_rsq_f32_e32 v64, v64
	s_nop 0
	v_mul_f32_e32 v120, 0x45800000, v64
	v_cndmask_b32_e32 v64, v64, v120, vcc
	s_and_saveexec_b64 s[20:21], s[2:3]
	s_cbranch_execz .LBB0_589
	v_div_scale_f32 v120, s[22:23], v64, v64, 1.0
	v_rcp_f32_e32 v121, v120
	v_div_scale_f32 v122, vcc, 1.0, v64, 1.0
	s_lshl_b64 s[22:23], s[10:11], 2
	v_fma_f32 v123, -v120, v121, 1.0
	v_fmac_f32_e32 v121, v123, v121
	v_mul_f32_e32 v123, v122, v121
	v_fma_f32 v124, -v120, v123, v122
	v_fmac_f32_e32 v123, v124, v121
	v_fma_f32 v120, -v120, v123, v122
	v_div_fmas_f32 v120, v120, v121, v123
	s_add_u32 s22, s30, s22
	v_div_fixup_f32 v120, v120, v64, 1.0
	s_addc_u32 s23, s31, s23
	global_store_dword v65, v120, s[22:23]

.LBB0_590:
	v_pk_mul_f32 v[120:121], v[100:101], v[100:101]
	v_pk_mul_f32 v[122:123], v[86:87], v[86:87]
	v_mul_f32_e32 v64, v82, v82
	v_pk_mov_b32 v[124:125], v[122:123], v[120:121] op_sel:[1,0]
	v_mov_b32_e32 v123, v121
	v_pk_add_f32 v[120:121], v[124:125], v[122:123]
	v_pk_mul_f32 v[122:123], v[106:107], v[106:107]
	v_pk_mul_f32 v[124:125], v[84:85], v[84:85]
	v_pk_add_f32 v[120:121], v[120:121], v[120:121] op_sel_hi:[0,1]
	v_pk_mov_b32 v[126:127], v[124:125], v[122:123] op_sel:[1,0]
	v_mov_b32_e32 v125, v123
	v_pk_add_f32 v[122:123], v[126:127], v[124:125]
	v_pk_fma_f32 v[124:125], v[82:83], v[82:83], v[64:65] op_sel_hi:[1,1,0]
	v_mul_f32_e32 v64, v112, v112
	v_pk_add_f32 v[122:123], v[122:123], v[122:123] op_sel_hi:[0,1]
	v_pk_fma_f32 v[126:127], v[112:113], v[112:113], v[64:65] op_sel_hi:[1,1,0]
	v_mul_f32_e32 v124, v80, v80
	v_mul_f32_e32 v126, v81, v81
	v_mul_f32_e32 v122, v116, v116
	v_mul_f32_e32 v120, v117, v117
	v_pk_add_f32 v[124:125], v[124:125], v[126:127]
	v_pk_add_f32 v[120:121], v[122:123], v[120:121]
	s_ashr_i32 s15, s14, 31
	v_pk_add_f32 v[120:121], v[124:125], v[120:121]
	s_nop 0
	v_add_f32_e32 v64, v120, v121
	s_waitcnt lgkmcnt(0)
	s_nop 1
	v_add_f32_dpp v64, v64, v64 quad_perm:[1,0,3,2] row_mask:0xf bank_mask:0xf
	s_waitcnt lgkmcnt(0)
	s_nop 1
	v_add_f32_dpp v64, v64, v64 quad_perm:[2,3,0,1] row_mask:0xf bank_mask:0xf
	s_waitcnt lgkmcnt(0)
	s_nop 1
	v_add_f32_dpp v64, v64, v64 row_half_mirror row_mask:0xf bank_mask:0xf
	s_waitcnt lgkmcnt(0)
	s_nop 1
	v_add_f32_dpp v64, v64, v64 row_mirror row_mask:0xf bank_mask:0xf
	s_waitcnt lgkmcnt(0)
	v_mov_b32_e32 v120, v64
	s_nop 1
	v_permlane16_swap_b32_e32 v64, v120
	v_add_f32_e32 v64, v64, v120
	s_waitcnt lgkmcnt(0)
	v_mov_b32_e32 v120, v64
	s_nop 1
	v_permlane32_swap_b32_e32 v64, v120
	v_add_f32_e32 v64, v64, v120
	v_fmamk_f32 v64, v64, 0x3a800000, v142
	v_mul_f32_e32 v120, 0x4b800000, v64
	v_cmp_gt_f32_e32 vcc, s7, v64
	s_nop 1
	v_cndmask_b32_e32 v64, v64, v120, vcc
	v_rsq_f32_e32 v64, v64
	s_nop 0
	v_mul_f32_e32 v120, 0x45800000, v64
	v_cndmask_b32_e32 v64, v64, v120, vcc
	v_pk_mul_f32 v[120:121], v[64:65], v[86:87] op_sel_hi:[0,1]
	v_pk_mul_f32 v[122:123], v[64:65], v[100:101] op_sel_hi:[0,1]
	v_pk_mul_f32 v[124:125], v[64:65], v[84:85] op_sel_hi:[0,1]
	v_pk_mul_f32 v[126:127], v[64:65], v[106:107] op_sel_hi:[0,1]
	v_pk_fma_f32 v[34:35], v[2:3], v[122:123], v[34:35]
	v_pk_fma_f32 v[32:33], v[0:1], v[120:121], v[32:33]
	v_pk_fma_f32 v[38:39], v[6:7], v[126:127], v[38:39]
	v_pk_fma_f32 v[36:37], v[4:5], v[124:125], v[36:37]
	v_pk_mul_f32 v[120:121], v[34:35], v[34:35]
	v_pk_mul_f32 v[122:123], v[32:33], v[32:33]
	v_pk_mul_f32 v[124:125], v[38:39], v[38:39]
	v_pk_mul_f32 v[126:127], v[36:37], v[36:37]
	v_pk_mov_b32 v[128:129], v[122:123], v[120:121] op_sel:[1,0]
	v_mov_b32_e32 v123, v121
	v_pk_add_f32 v[120:121], v[128:129], v[122:123]
	v_pk_mov_b32 v[122:123], v[126:127], v[124:125] op_sel:[1,0]
	v_mov_b32_e32 v127, v125
	v_pk_mul_f32 v[124:125], v[64:65], v[82:83] op_sel_hi:[0,1]
	v_pk_add_f32 v[120:121], v[120:121], v[120:121] op_sel_hi:[0,1]
	v_pk_add_f32 v[122:123], v[122:123], v[126:127]
	v_pk_mul_f32 v[126:127], v[64:65], v[112:113] op_sel_hi:[0,1]
	v_pk_fma_f32 v[44:45], v[8:9], v[124:125], v[44:45]
	v_pk_fma_f32 v[46:47], v[10:11], v[126:127], v[46:47]
	v_mul_f32_e32 v120, v44, v44
	v_pk_fma_f32 v[124:125], v[44:45], v[44:45], v[120:121] op_sel_hi:[1,1,0]
	v_mul_f32_e32 v120, v46, v46
	v_pk_mul_f32 v[128:129], v[64:65], v[80:81] op_sel_hi:[0,1]
	v_pk_mul_f32 v[130:131], v[64:65], v[116:117] op_sel_hi:[0,1]
	v_pk_add_f32 v[122:123], v[122:123], v[122:123] op_sel_hi:[0,1]
	v_pk_fma_f32 v[126:127], v[46:47], v[46:47], v[120:121] op_sel_hi:[1,1,0]
	v_pk_fma_f32 v[54:55], v[14:15], v[130:131], v[54:55]
	v_pk_fma_f32 v[52:53], v[12:13], v[128:129], v[52:53]
	v_mul_f32_e32 v120, v54, v54
	v_mul_f32_e32 v124, v52, v52
	v_mul_f32_e32 v126, v53, v53
	v_mul_f32_e32 v122, v55, v55
	v_pk_add_f32 v[124:125], v[124:125], v[126:127]
	v_pk_add_f32 v[120:121], v[120:121], v[122:123]
	s_nop 0
	v_pk_add_f32 v[120:121], v[124:125], v[120:121]
	s_nop 0
	v_add_f32_e32 v64, v120, v121
	s_waitcnt lgkmcnt(0)
	s_nop 1
	v_add_f32_dpp v64, v64, v64 quad_perm:[1,0,3,2] row_mask:0xf bank_mask:0xf
	s_waitcnt lgkmcnt(0)
	s_nop 1
	v_add_f32_dpp v64, v64, v64 quad_perm:[2,3,0,1] row_mask:0xf bank_mask:0xf
	s_waitcnt lgkmcnt(0)
	s_nop 1
	v_add_f32_dpp v64, v64, v64 row_half_mirror row_mask:0xf bank_mask:0xf
	s_waitcnt lgkmcnt(0)
	s_nop 1
	v_add_f32_dpp v64, v64, v64 row_mirror row_mask:0xf bank_mask:0xf
	s_waitcnt lgkmcnt(0)
	v_mov_b32_e32 v120, v64
	s_nop 1
	v_permlane16_swap_b32_e32 v64, v120
	v_add_f32_e32 v64, v64, v120
	s_waitcnt lgkmcnt(0)
	v_mov_b32_e32 v120, v64
	s_nop 1
	v_permlane32_swap_b32_e32 v64, v120
	v_add_f32_e32 v64, v64, v120
	v_fmamk_f32 v64, v64, 0x3a800000, v142
	v_mul_f32_e32 v120, 0x4b800000, v64
	v_cmp_gt_f32_e32 vcc, s7, v64
	s_nop 1
	v_cndmask_b32_e32 v64, v64, v120, vcc
	v_rsq_f32_e32 v64, v64
	s_nop 0
	v_mul_f32_e32 v120, 0x45800000, v64
	v_cndmask_b32_e32 v64, v64, v120, vcc
	s_and_saveexec_b64 s[18:19], s[2:3]
	s_cbranch_execz .LBB0_592
	v_div_scale_f32 v120, s[20:21], v64, v64, 1.0
	v_rcp_f32_e32 v121, v120
	v_div_scale_f32 v122, vcc, 1.0, v64, 1.0
	s_lshl_b64 s[20:21], s[14:15], 2
	v_fma_f32 v123, -v120, v121, 1.0
	v_fmac_f32_e32 v121, v123, v121
	v_mul_f32_e32 v123, v122, v121
	v_fma_f32 v124, -v120, v123, v122
	v_fmac_f32_e32 v123, v124, v121
	v_fma_f32 v120, -v120, v123, v122
	v_div_fmas_f32 v120, v120, v121, v123
	s_add_u32 s20, s30, s20
	v_div_fixup_f32 v120, v120, v64, 1.0
	s_addc_u32 s21, s31, s21
	global_store_dword v65, v120, s[20:21]

.LBB0_593:
	v_pk_mul_f32 v[120:121], v[96:97], v[96:97]
	v_pk_mul_f32 v[122:123], v[78:79], v[78:79]
	v_mul_f32_e32 v64, v74, v74
	v_pk_mov_b32 v[124:125], v[122:123], v[120:121] op_sel:[1,0]
	v_mov_b32_e32 v123, v121
	v_pk_add_f32 v[120:121], v[124:125], v[122:123]
	v_pk_mul_f32 v[122:123], v[98:99], v[98:99]
	v_pk_mul_f32 v[124:125], v[76:77], v[76:77]
	v_pk_add_f32 v[120:121], v[120:121], v[120:121] op_sel_hi:[0,1]
	v_pk_mov_b32 v[126:127], v[124:125], v[122:123] op_sel:[1,0]
	v_mov_b32_e32 v125, v123
	v_pk_add_f32 v[122:123], v[126:127], v[124:125]
	v_pk_fma_f32 v[124:125], v[74:75], v[74:75], v[64:65] op_sel_hi:[1,1,0]
	v_mul_f32_e32 v64, v102, v102
	v_pk_add_f32 v[122:123], v[122:123], v[122:123] op_sel_hi:[0,1]
	v_pk_fma_f32 v[126:127], v[102:103], v[102:103], v[64:65] op_sel_hi:[1,1,0]
	v_mul_f32_e32 v124, v72, v72
	v_mul_f32_e32 v126, v73, v73
	v_mul_f32_e32 v122, v108, v108
	v_mul_f32_e32 v120, v109, v109
	v_pk_add_f32 v[124:125], v[124:125], v[126:127]
	v_pk_add_f32 v[120:121], v[122:123], v[120:121]
	s_ashr_i32 s13, s12, 31
	v_pk_add_f32 v[120:121], v[124:125], v[120:121]
	s_nop 0
	v_add_f32_e32 v64, v120, v121
	s_waitcnt lgkmcnt(0)
	s_nop 1
	v_add_f32_dpp v64, v64, v64 quad_perm:[1,0,3,2] row_mask:0xf bank_mask:0xf
	s_waitcnt lgkmcnt(0)
	s_nop 1
	v_add_f32_dpp v64, v64, v64 quad_perm:[2,3,0,1] row_mask:0xf bank_mask:0xf
	s_waitcnt lgkmcnt(0)
	s_nop 1
	v_add_f32_dpp v64, v64, v64 row_half_mirror row_mask:0xf bank_mask:0xf
	s_waitcnt lgkmcnt(0)
	s_nop 1
	v_add_f32_dpp v64, v64, v64 row_mirror row_mask:0xf bank_mask:0xf
	s_waitcnt lgkmcnt(0)
	v_mov_b32_e32 v120, v64
	s_nop 1
	v_permlane16_swap_b32_e32 v64, v120
	v_add_f32_e32 v64, v64, v120
	s_waitcnt lgkmcnt(0)
	v_mov_b32_e32 v120, v64
	s_nop 1
	v_permlane32_swap_b32_e32 v64, v120
	v_add_f32_e32 v64, v64, v120
	v_fmamk_f32 v64, v64, 0x3a800000, v142
	v_mul_f32_e32 v120, 0x4b800000, v64
	v_cmp_gt_f32_e32 vcc, s7, v64
	s_nop 1
	v_cndmask_b32_e32 v64, v64, v120, vcc
	v_rsq_f32_e32 v64, v64
	s_nop 0
	v_mul_f32_e32 v120, 0x45800000, v64
	v_cndmask_b32_e32 v64, v64, v120, vcc
	v_pk_mul_f32 v[120:121], v[64:65], v[78:79] op_sel_hi:[0,1]
	v_pk_mul_f32 v[122:123], v[64:65], v[96:97] op_sel_hi:[0,1]
	v_pk_mul_f32 v[124:125], v[64:65], v[76:77] op_sel_hi:[0,1]
	v_pk_mul_f32 v[126:127], v[64:65], v[98:99] op_sel_hi:[0,1]
	v_pk_fma_f32 v[18:19], v[2:3], v[122:123], v[18:19]
	v_pk_fma_f32 v[16:17], v[0:1], v[120:121], v[16:17]
	v_pk_fma_f32 v[22:23], v[6:7], v[126:127], v[22:23]
	v_pk_fma_f32 v[20:21], v[4:5], v[124:125], v[20:21]
	v_pk_mul_f32 v[120:121], v[18:19], v[18:19]
	v_pk_mul_f32 v[122:123], v[16:17], v[16:17]
	v_pk_mul_f32 v[124:125], v[22:23], v[22:23]
	v_pk_mul_f32 v[126:127], v[20:21], v[20:21]
	v_pk_mov_b32 v[128:129], v[122:123], v[120:121] op_sel:[1,0]
	v_mov_b32_e32 v123, v121
	v_pk_add_f32 v[120:121], v[128:129], v[122:123]
	v_pk_mov_b32 v[122:123], v[126:127], v[124:125] op_sel:[1,0]
	v_mov_b32_e32 v127, v125
	v_pk_mul_f32 v[124:125], v[64:65], v[74:75] op_sel_hi:[0,1]
	v_pk_add_f32 v[120:121], v[120:121], v[120:121] op_sel_hi:[0,1]
	v_pk_add_f32 v[122:123], v[122:123], v[126:127]
	v_pk_mul_f32 v[126:127], v[64:65], v[102:103] op_sel_hi:[0,1]
	v_pk_fma_f32 v[24:25], v[8:9], v[124:125], v[24:25]
	v_pk_fma_f32 v[26:27], v[10:11], v[126:127], v[26:27]
	v_mul_f32_e32 v120, v24, v24
	v_pk_fma_f32 v[124:125], v[24:25], v[24:25], v[120:121] op_sel_hi:[1,1,0]
	v_mul_f32_e32 v120, v26, v26
	v_pk_mul_f32 v[128:129], v[64:65], v[72:73] op_sel_hi:[0,1]
	v_pk_mul_f32 v[130:131], v[64:65], v[108:109] op_sel_hi:[0,1]
	v_pk_add_f32 v[122:123], v[122:123], v[122:123] op_sel_hi:[0,1]
	v_pk_fma_f32 v[126:127], v[26:27], v[26:27], v[120:121] op_sel_hi:[1,1,0]
	v_pk_fma_f32 v[30:31], v[14:15], v[130:131], v[30:31]
	v_pk_fma_f32 v[28:29], v[12:13], v[128:129], v[28:29]
	v_mul_f32_e32 v120, v30, v30
	v_mul_f32_e32 v124, v28, v28
	v_mul_f32_e32 v126, v29, v29
	v_mul_f32_e32 v122, v31, v31
	v_pk_add_f32 v[124:125], v[124:125], v[126:127]
	v_pk_add_f32 v[120:121], v[120:121], v[122:123]
	s_nop 0
	v_pk_add_f32 v[120:121], v[124:125], v[120:121]
	s_nop 0
	v_add_f32_e32 v64, v120, v121
	s_waitcnt lgkmcnt(0)
	s_nop 1
	v_add_f32_dpp v64, v64, v64 quad_perm:[1,0,3,2] row_mask:0xf bank_mask:0xf
	s_waitcnt lgkmcnt(0)
	s_nop 1
	v_add_f32_dpp v64, v64, v64 quad_perm:[2,3,0,1] row_mask:0xf bank_mask:0xf
	s_waitcnt lgkmcnt(0)
	s_nop 1
	v_add_f32_dpp v64, v64, v64 row_half_mirror row_mask:0xf bank_mask:0xf
	s_waitcnt lgkmcnt(0)
	s_nop 1
	v_add_f32_dpp v64, v64, v64 row_mirror row_mask:0xf bank_mask:0xf
	s_waitcnt lgkmcnt(0)
	v_mov_b32_e32 v120, v64
	s_nop 1
	v_permlane16_swap_b32_e32 v64, v120
	v_add_f32_e32 v64, v64, v120
	s_waitcnt lgkmcnt(0)
	v_mov_b32_e32 v120, v64
	s_nop 1
	v_permlane32_swap_b32_e32 v64, v120
	v_add_f32_e32 v64, v64, v120
	v_fmamk_f32 v64, v64, 0x3a800000, v142
	v_mul_f32_e32 v120, 0x4b800000, v64
	v_cmp_gt_f32_e32 vcc, s7, v64
	s_nop 1
	v_cndmask_b32_e32 v64, v64, v120, vcc
	v_rsq_f32_e32 v64, v64
	s_nop 0
	v_mul_f32_e32 v120, 0x45800000, v64
	v_cndmask_b32_e32 v64, v64, v120, vcc
	s_and_saveexec_b64 s[14:15], s[2:3]
	s_cbranch_execz .LBB0_574
	v_div_scale_f32 v120, s[16:17], v64, v64, 1.0
	v_rcp_f32_e32 v121, v120
	v_div_scale_f32 v122, vcc, 1.0, v64, 1.0
	s_lshl_b64 s[16:17], s[12:13], 2
	v_fma_f32 v123, -v120, v121, 1.0
	v_fmac_f32_e32 v121, v123, v121
	v_mul_f32_e32 v123, v122, v121
	v_fma_f32 v124, -v120, v123, v122
	v_fmac_f32_e32 v123, v124, v121
	v_fma_f32 v120, -v120, v123, v122
	v_div_fmas_f32 v120, v120, v121, v123
	s_add_u32 s16, s30, s16
	v_div_fixup_f32 v120, v120, v64, 1.0
	s_addc_u32 s17, s31, s17
	global_store_dword v65, v120, s[16:17]
	s_branch .LBB0_574

.LBB0_923:
	s_waitcnt vmcnt(0)
	v_lshlrev_b32_e32 v144, 16, v134
	v_and_b32_e32 v145, 0xffff0000, v134
	v_lshlrev_b32_e32 v134, 16, v135
	v_and_b32_e32 v135, 0xffff0000, v135
	v_lshlrev_b32_e32 v147, 16, v133
	v_lshlrev_b32_e32 v146, 16, v132
	v_and_b32_e32 v133, 0xffff0000, v133
	v_and_b32_e32 v132, 0xffff0000, v132
	v_lshlrev_b32_e32 v151, 16, v128
	v_and_b32_e32 v153, 0xffff0000, v128
	v_mul_f32_e32 v128, v135, v135
	v_mul_f32_e32 v150, v145, v145
	v_lshlrev_b32_e32 v154, 16, v129
	v_and_b32_e32 v155, 0xffff0000, v129
	v_pk_fma_f32 v[128:129], v[134:135], v[134:135], v[128:129] op_sel_hi:[1,1,0]
	v_pk_mul_f32 v[156:157], v[132:133], v[132:133]
	v_pk_fma_f32 v[158:159], v[144:145], v[144:145], v[150:151] op_sel_hi:[1,1,0]
	v_pk_fma_f32 v[156:157], v[146:147], v[146:147], v[156:157]
	v_mov_b32_e32 v150, v158
	v_mov_b32_e32 v160, v128
	v_mov_b32_e32 v161, v151
	v_and_b32_e32 v149, 0xffff0000, v130
	v_mul_f32_e32 v143, v153, v153
	v_pk_add_f32 v[128:129], v[158:159], v[128:129]
	v_pk_mul_f32 v[158:159], v[150:151], v[160:161]
	v_pk_add_f32 v[156:157], v[156:157], v[156:157] op_sel:[0,1] op_sel_hi:[1,0]
	v_lshlrev_b32_e32 v148, 16, v130
	v_lshlrev_b32_e32 v130, 16, v131
	v_and_b32_e32 v131, 0xffff0000, v131
	v_mov_b32_e32 v129, v159
	v_mov_b32_e32 v157, v143
	v_mul_f32_e32 v150, v149, v149
	v_pk_add_f32 v[128:129], v[128:129], v[156:157]
	v_pk_fma_f32 v[156:157], v[148:149], v[148:149], v[150:151] op_sel_hi:[1,1,0]
	v_mul_f32_e32 v150, v131, v131
	v_mul_f32_e32 v152, v154, v154
	v_mul_f32_e32 v162, v155, v155
	v_pk_fma_f32 v[158:159], v[130:131], v[130:131], v[150:151] op_sel_hi:[1,1,0]
	v_mov_b32_e32 v157, v152
	v_mov_b32_e32 v159, v162
	v_pk_add_f32 v[156:157], v[156:157], v[158:159]
	v_lshlrev_b32_e32 v158, 16, v122
	v_pk_add_f32 v[128:129], v[128:129], v[156:157]
	v_and_b32_e32 v159, 0xffff0000, v122
	v_add_f32_e32 v128, v128, v129
	v_lshlrev_b32_e32 v160, 16, v123
	v_and_b32_e32 v161, 0xffff0000, v123
	v_lshlrev_b32_e32 v162, 16, v120
	v_and_b32_e32 v163, 0xffff0000, v120
	s_waitcnt lgkmcnt(0)
	s_nop 1
	v_add_f32_dpp v128, v128, v128 quad_perm:[1,0,3,2] row_mask:0xf bank_mask:0xf
	v_lshlrev_b32_e32 v164, 16, v121
	v_and_b32_e32 v165, 0xffff0000, v121
	v_lshlrev_b32_e32 v156, 16, v124
	v_and_b32_e32 v157, 0xffff0000, v124
	s_waitcnt lgkmcnt(0)
	s_nop 1
	v_add_f32_dpp v129, v128, v128 quad_perm:[2,3,0,1] row_mask:0xf bank_mask:0xf
	v_lshlrev_b32_e32 v128, 16, v126
	v_lshlrev_b32_e32 v124, 16, v125
	v_and_b32_e32 v125, 0xffff0000, v125
	v_mov_b32_e32 v152, v151
	s_waitcnt lgkmcnt(0)
	s_nop 1
	v_add_f32_dpp v143, v129, v129 row_half_mirror row_mask:0xf bank_mask:0xf
	v_and_b32_e32 v129, 0xffff0000, v126
	v_lshlrev_b32_e32 v126, 16, v127
	v_and_b32_e32 v127, 0xffff0000, v127
	s_lshl_b64 s[6:7], s[6:7], 12
	s_waitcnt lgkmcnt(0)
	s_nop 1
	v_add_f32_dpp v143, v143, v143 row_mirror row_mask:0xf bank_mask:0xf
	s_waitcnt lgkmcnt(0)
	v_mov_b32_e32 v150, v143
	s_nop 1
	v_permlane16_swap_b32_e32 v143, v150
	v_add_f32_e32 v143, v143, v150
	s_waitcnt lgkmcnt(0)
	v_mov_b32_e32 v122, v143
	v_mov_b32_e32 v150, v143
	s_nop 1
	v_permlane32_swap_b32_e32 v122, v150
	v_add_f32_e32 v122, v122, v150
	v_fmamk_f32 v122, v122, 0x3a800000, v142
	v_mul_f32_e32 v123, 0x4b800000, v122
	v_cmp_gt_f32_e32 vcc, s1, v122
	s_nop 1
	v_cndmask_b32_e32 v122, v122, v123, vcc
	v_rsq_f32_e32 v122, v122
	s_nop 0
	v_mul_f32_e32 v120, 0x45800000, v122
	v_cndmask_b32_e32 v150, v122, v120, vcc
	v_pk_mul_f32 v[120:121], v[150:151], v[134:135] op_sel_hi:[0,1]
	v_pk_mul_f32 v[122:123], v[150:151], v[144:145] op_sel_hi:[0,1]
	v_pk_mul_f32 v[120:121], v[2:3], v[120:121]
	v_pk_mul_f32 v[134:135], v[0:1], v[122:123]
	v_pk_fma_f32 v[122:123], v[64:65], v[126:127], v[120:121] op_sel_hi:[0,1,1]
	v_mov_b32_e32 v126, v147
	v_mov_b32_e32 v127, v133
	v_mov_b32_e32 v147, v132
	v_pk_fma_f32 v[120:121], v[64:65], v[128:129], v[134:135] op_sel_hi:[0,1,1]
	v_pk_mul_f32 v[126:127], v[150:151], v[126:127] op_sel_hi:[0,1]
	v_pk_mul_f32 v[128:129], v[150:151], v[146:147] op_sel_hi:[0,1]
	v_pk_mul_f32 v[128:129], v[4:5], v[128:129]
	v_pk_mul_f32 v[126:127], v[6:7], v[126:127]
	v_pk_mul_f32 v[134:135], v[150:151], v[152:153] op_sel_hi:[0,1]
	v_pk_fma_f32 v[126:127], v[64:65], v[124:125], v[126:127] op_sel_hi:[0,1,1]
	v_pk_fma_f32 v[124:125], v[64:65], v[156:157], v[128:129] op_sel_hi:[0,1,1]
	v_pk_mul_f32 v[128:129], v[150:151], v[130:131] op_sel_hi:[0,1]
	v_pk_mul_f32 v[130:131], v[150:151], v[148:149] op_sel_hi:[0,1]
	v_pk_mul_f32 v[132:133], v[8:9], v[130:131]
	v_pk_mul_f32 v[128:129], v[10:11], v[128:129]
	v_pk_mul_f32 v[144:145], v[12:13], v[134:135]
	v_pk_fma_f32 v[130:131], v[64:65], v[160:161], v[128:129] op_sel_hi:[0,1,1]
	v_pk_fma_f32 v[128:129], v[64:65], v[158:159], v[132:133] op_sel_hi:[0,1,1]
	v_pk_mul_f32 v[132:133], v[150:151], v[154:155] op_sel_hi:[0,1]
	v_pk_mul_f32 v[132:133], v[14:15], v[132:133]
	s_andn2_b64 vcc, exec, s[10:11]
	v_pk_fma_f32 v[134:135], v[64:65], v[164:165], v[132:133] op_sel_hi:[0,1,1]
	v_pk_fma_f32 v[132:133], v[64:65], v[162:163], v[144:145] op_sel_hi:[0,1,1]
	v_lshl_add_u64 v[144:145], v[70:71], 0, s[6:7]
	global_store_dwordx4 v[144:145], v[120:123], off nt
	global_store_dwordx4 v[144:145], v[124:127], off offset:1024 nt
	global_store_dwordx4 v[144:145], v[128:131], off offset:2048 nt
	global_store_dwordx4 v[144:145], v[132:135], off offset:3072 nt
	s_cbranch_vccz .LBB0_926
	s_andn2_b64 vcc, exec, s[14:15]
	s_cbranch_vccz .LBB0_927

.LBB0_926:
	v_pk_mul_f32 v[120:121], v[104:105], v[104:105]
	v_pk_mul_f32 v[122:123], v[94:95], v[94:95]
	v_mul_f32_e32 v64, v90, v90
	v_pk_mov_b32 v[124:125], v[122:123], v[120:121] op_sel:[1,0]
	v_mov_b32_e32 v123, v121
	v_pk_add_f32 v[120:121], v[124:125], v[122:123]
	v_pk_mul_f32 v[122:123], v[110:111], v[110:111]
	v_pk_mul_f32 v[124:125], v[92:93], v[92:93]
	v_pk_add_f32 v[120:121], v[120:121], v[120:121] op_sel_hi:[0,1]
	v_pk_mov_b32 v[126:127], v[124:125], v[122:123] op_sel:[1,0]
	v_mov_b32_e32 v125, v123
	v_pk_add_f32 v[122:123], v[126:127], v[124:125]
	v_pk_fma_f32 v[124:125], v[90:91], v[90:91], v[64:65] op_sel_hi:[1,1,0]
	v_mul_f32_e32 v64, v114, v114
	v_pk_add_f32 v[122:123], v[122:123], v[122:123] op_sel_hi:[0,1]
	v_pk_fma_f32 v[126:127], v[114:115], v[114:115], v[64:65] op_sel_hi:[1,1,0]
	v_mul_f32_e32 v124, v88, v88
	v_mul_f32_e32 v126, v89, v89
	v_mul_f32_e32 v122, v118, v118
	v_mul_f32_e32 v120, v119, v119
	v_pk_add_f32 v[124:125], v[124:125], v[126:127]
	v_pk_add_f32 v[120:121], v[122:123], v[120:121]
	s_ashr_i32 s5, s4, 31
	v_pk_add_f32 v[120:121], v[124:125], v[120:121]
	s_lshl_b64 s[6:7], s[4:5], 12
	v_add_f32_e32 v64, v120, v121
	s_waitcnt lgkmcnt(0)
	s_nop 1
	v_add_f32_dpp v64, v64, v64 quad_perm:[1,0,3,2] row_mask:0xf bank_mask:0xf
	s_waitcnt lgkmcnt(0)
	s_nop 1
	v_add_f32_dpp v64, v64, v64 quad_perm:[2,3,0,1] row_mask:0xf bank_mask:0xf
	s_waitcnt lgkmcnt(0)
	s_nop 1
	v_add_f32_dpp v64, v64, v64 row_half_mirror row_mask:0xf bank_mask:0xf
	s_waitcnt lgkmcnt(0)
	s_nop 1
	v_add_f32_dpp v64, v64, v64 row_mirror row_mask:0xf bank_mask:0xf
	s_waitcnt lgkmcnt(0)
	v_mov_b32_e32 v120, v64
	s_nop 1
	v_permlane16_swap_b32_e32 v64, v120
	v_add_f32_e32 v64, v64, v120
	s_waitcnt lgkmcnt(0)
	v_mov_b32_e32 v120, v64
	s_nop 1
	v_permlane32_swap_b32_e32 v64, v120
	v_add_f32_e32 v64, v64, v120
	v_fmamk_f32 v64, v64, 0x3a800000, v142
	v_mul_f32_e32 v120, 0x4b800000, v64
	v_cmp_gt_f32_e32 vcc, s1, v64
	s_nop 1
	v_cndmask_b32_e32 v64, v64, v120, vcc
	v_rsq_f32_e32 v64, v64
	s_nop 0
	v_mul_f32_e32 v120, 0x45800000, v64
	v_cndmask_b32_e32 v64, v64, v120, vcc
	v_pk_mul_f32 v[120:121], v[64:65], v[94:95] op_sel_hi:[0,1]
	v_pk_mul_f32 v[122:123], v[64:65], v[104:105] op_sel_hi:[0,1]
	v_pk_mul_f32 v[124:125], v[64:65], v[92:93] op_sel_hi:[0,1]
	v_pk_mul_f32 v[126:127], v[64:65], v[110:111] op_sel_hi:[0,1]
	v_pk_mul_f32 v[128:129], v[64:65], v[90:91] op_sel_hi:[0,1]
	v_pk_mul_f32 v[130:131], v[64:65], v[114:115] op_sel_hi:[0,1]
	v_pk_fma_f32 v[46:47], v[2:3], v[122:123], v[46:47]
	v_pk_fma_f32 v[44:45], v[0:1], v[120:121], v[44:45]
	v_pk_mul_f32 v[120:121], v[64:65], v[88:89] op_sel_hi:[0,1]
	v_pk_mul_f32 v[122:123], v[64:65], v[118:119] op_sel_hi:[0,1]
	v_pk_fma_f32 v[54:55], v[6:7], v[126:127], v[54:55]
	v_pk_fma_f32 v[52:53], v[4:5], v[124:125], v[52:53]
	v_pk_fma_f32 v[58:59], v[10:11], v[130:131], v[58:59]
	v_pk_fma_f32 v[56:57], v[8:9], v[128:129], v[56:57]
	v_pk_fma_f32 v[62:63], v[14:15], v[122:123], v[62:63]
	v_pk_fma_f32 v[60:61], v[12:13], v[120:121], v[60:61]
	v_lshl_add_u64 v[120:121], v[70:71], 0, s[6:7]
	global_store_dwordx4 v[120:121], v[44:47], off nt
	global_store_dwordx4 v[120:121], v[52:55], off offset:1024 nt
	global_store_dwordx4 v[120:121], v[56:59], off offset:2048 nt
	global_store_dwordx4 v[120:121], v[60:63], off offset:3072 nt
	s_andn2_b64 vcc, exec, s[14:15]
	s_cbranch_vccnz .LBB0_925
.LBB0_927:
	v_pk_mul_f32 v[120:121], v[100:101], v[100:101]
	v_pk_mul_f32 v[122:123], v[86:87], v[86:87]
	v_mul_f32_e32 v64, v82, v82
	v_pk_mov_b32 v[124:125], v[122:123], v[120:121] op_sel:[1,0]
	v_mov_b32_e32 v123, v121
	v_pk_add_f32 v[120:121], v[124:125], v[122:123]
	v_pk_mul_f32 v[122:123], v[106:107], v[106:107]
	v_pk_mul_f32 v[124:125], v[84:85], v[84:85]
	v_pk_add_f32 v[120:121], v[120:121], v[120:121] op_sel_hi:[0,1]
	v_pk_mov_b32 v[126:127], v[124:125], v[122:123] op_sel:[1,0]
	v_mov_b32_e32 v125, v123
	v_pk_add_f32 v[122:123], v[126:127], v[124:125]
	v_pk_fma_f32 v[124:125], v[82:83], v[82:83], v[64:65] op_sel_hi:[1,1,0]
	v_mul_f32_e32 v64, v112, v112
	v_pk_add_f32 v[122:123], v[122:123], v[122:123] op_sel_hi:[0,1]
	v_pk_fma_f32 v[126:127], v[112:113], v[112:113], v[64:65] op_sel_hi:[1,1,0]
	v_mul_f32_e32 v124, v80, v80
	v_mul_f32_e32 v126, v81, v81
	v_mul_f32_e32 v122, v116, v116
	v_mul_f32_e32 v120, v117, v117
	v_pk_add_f32 v[124:125], v[124:125], v[126:127]
	v_pk_add_f32 v[120:121], v[122:123], v[120:121]
	s_ashr_i32 s9, s8, 31
	v_pk_add_f32 v[120:121], v[124:125], v[120:121]
	s_lshl_b64 s[6:7], s[8:9], 12
	v_add_f32_e32 v64, v120, v121
	s_waitcnt lgkmcnt(0)
	s_nop 1
	v_add_f32_dpp v64, v64, v64 quad_perm:[1,0,3,2] row_mask:0xf bank_mask:0xf
	s_waitcnt lgkmcnt(0)
	s_nop 1
	v_add_f32_dpp v64, v64, v64 quad_perm:[2,3,0,1] row_mask:0xf bank_mask:0xf
	s_waitcnt lgkmcnt(0)
	s_nop 1
	v_add_f32_dpp v64, v64, v64 row_half_mirror row_mask:0xf bank_mask:0xf
	s_waitcnt lgkmcnt(0)
	s_nop 1
	v_add_f32_dpp v64, v64, v64 row_mirror row_mask:0xf bank_mask:0xf
	s_waitcnt lgkmcnt(0)
	v_mov_b32_e32 v120, v64
	s_nop 1
	v_permlane16_swap_b32_e32 v64, v120
	v_add_f32_e32 v64, v64, v120
	s_waitcnt lgkmcnt(0)
	v_mov_b32_e32 v120, v64
	s_nop 1
	v_permlane32_swap_b32_e32 v64, v120
	v_add_f32_e32 v64, v64, v120
	v_fmamk_f32 v64, v64, 0x3a800000, v142
	v_mul_f32_e32 v120, 0x4b800000, v64
	v_cmp_gt_f32_e32 vcc, s1, v64
	s_nop 1
	v_cndmask_b32_e32 v64, v64, v120, vcc
	v_rsq_f32_e32 v64, v64
	s_nop 0
	v_mul_f32_e32 v120, 0x45800000, v64
	v_cndmask_b32_e32 v64, v64, v120, vcc
	v_pk_mul_f32 v[120:121], v[64:65], v[86:87] op_sel_hi:[0,1]
	v_pk_mul_f32 v[122:123], v[64:65], v[100:101] op_sel_hi:[0,1]
	v_pk_mul_f32 v[124:125], v[64:65], v[84:85] op_sel_hi:[0,1]
	v_pk_mul_f32 v[126:127], v[64:65], v[106:107] op_sel_hi:[0,1]
	v_pk_mul_f32 v[128:129], v[64:65], v[82:83] op_sel_hi:[0,1]
	v_pk_mul_f32 v[130:131], v[64:65], v[112:113] op_sel_hi:[0,1]
	v_pk_fma_f32 v[34:35], v[2:3], v[122:123], v[34:35]
	v_pk_fma_f32 v[32:33], v[0:1], v[120:121], v[32:33]
	v_pk_mul_f32 v[120:121], v[64:65], v[80:81] op_sel_hi:[0,1]
	v_pk_mul_f32 v[122:123], v[64:65], v[116:117] op_sel_hi:[0,1]
	v_pk_fma_f32 v[38:39], v[6:7], v[126:127], v[38:39]
	v_pk_fma_f32 v[36:37], v[4:5], v[124:125], v[36:37]
	v_pk_fma_f32 v[42:43], v[10:11], v[130:131], v[42:43]
	v_pk_fma_f32 v[40:41], v[8:9], v[128:129], v[40:41]
	v_pk_fma_f32 v[50:51], v[14:15], v[122:123], v[50:51]
	v_pk_fma_f32 v[48:49], v[12:13], v[120:121], v[48:49]
	v_lshl_add_u64 v[120:121], v[70:71], 0, s[6:7]
	global_store_dwordx4 v[120:121], v[32:35], off nt
	global_store_dwordx4 v[120:121], v[36:39], off offset:1024 nt
	global_store_dwordx4 v[120:121], v[40:43], off offset:2048 nt
	global_store_dwordx4 v[120:121], v[48:51], off offset:3072 nt
	s_andn2_b64 vcc, exec, s[16:17]
	s_cbranch_vccnz .LBB0_916
.LBB0_928:
	v_pk_mul_f32 v[120:121], v[96:97], v[96:97]
	v_pk_mul_f32 v[122:123], v[78:79], v[78:79]
	v_mul_f32_e32 v64, v74, v74
	v_pk_mov_b32 v[124:125], v[122:123], v[120:121] op_sel:[1,0]
	v_mov_b32_e32 v123, v121
	v_pk_add_f32 v[120:121], v[124:125], v[122:123]
	v_pk_mul_f32 v[122:123], v[98:99], v[98:99]
	v_pk_mul_f32 v[124:125], v[76:77], v[76:77]
	v_pk_add_f32 v[120:121], v[120:121], v[120:121] op_sel_hi:[0,1]
	v_pk_mov_b32 v[126:127], v[124:125], v[122:123] op_sel:[1,0]
	v_mov_b32_e32 v125, v123
	v_pk_add_f32 v[122:123], v[126:127], v[124:125]
	v_pk_fma_f32 v[124:125], v[74:75], v[74:75], v[64:65] op_sel_hi:[1,1,0]
	v_mul_f32_e32 v64, v102, v102
	v_pk_add_f32 v[122:123], v[122:123], v[122:123] op_sel_hi:[0,1]
	v_pk_fma_f32 v[126:127], v[102:103], v[102:103], v[64:65] op_sel_hi:[1,1,0]
	v_mul_f32_e32 v124, v72, v72
	v_mul_f32_e32 v126, v73, v73
	v_mul_f32_e32 v122, v108, v108
	v_mul_f32_e32 v120, v109, v109
	v_pk_add_f32 v[124:125], v[124:125], v[126:127]
	v_pk_add_f32 v[120:121], v[122:123], v[120:121]
	s_ashr_i32 s13, s12, 31
	v_pk_add_f32 v[120:121], v[124:125], v[120:121]
	s_lshl_b64 s[6:7], s[12:13], 12
	v_add_f32_e32 v64, v120, v121
	s_waitcnt lgkmcnt(0)
	s_nop 1
	v_add_f32_dpp v64, v64, v64 quad_perm:[1,0,3,2] row_mask:0xf bank_mask:0xf
	s_waitcnt lgkmcnt(0)
	s_nop 1
	v_add_f32_dpp v64, v64, v64 quad_perm:[2,3,0,1] row_mask:0xf bank_mask:0xf
	s_waitcnt lgkmcnt(0)
	s_nop 1
	v_add_f32_dpp v64, v64, v64 row_half_mirror row_mask:0xf bank_mask:0xf
	s_waitcnt lgkmcnt(0)
	s_nop 1
	v_add_f32_dpp v64, v64, v64 row_mirror row_mask:0xf bank_mask:0xf
	s_waitcnt lgkmcnt(0)
	v_mov_b32_e32 v120, v64
	s_nop 1
	v_permlane16_swap_b32_e32 v64, v120
	v_add_f32_e32 v64, v64, v120
	s_waitcnt lgkmcnt(0)
	v_mov_b32_e32 v120, v64
	s_nop 1
	v_permlane32_swap_b32_e32 v64, v120
	v_add_f32_e32 v64, v64, v120
	v_fmamk_f32 v64, v64, 0x3a800000, v142
	v_mul_f32_e32 v120, 0x4b800000, v64
	v_cmp_gt_f32_e32 vcc, s1, v64
	s_nop 1
	v_cndmask_b32_e32 v64, v64, v120, vcc
	v_rsq_f32_e32 v64, v64
	s_nop 0
	v_mul_f32_e32 v120, 0x45800000, v64
	v_cndmask_b32_e32 v64, v64, v120, vcc
	v_pk_mul_f32 v[120:121], v[64:65], v[78:79] op_sel_hi:[0,1]
	v_pk_mul_f32 v[122:123], v[64:65], v[96:97] op_sel_hi:[0,1]
	v_pk_mul_f32 v[124:125], v[64:65], v[76:77] op_sel_hi:[0,1]
	v_pk_mul_f32 v[126:127], v[64:65], v[98:99] op_sel_hi:[0,1]
	v_pk_mul_f32 v[128:129], v[64:65], v[74:75] op_sel_hi:[0,1]
	v_pk_mul_f32 v[130:131], v[64:65], v[102:103] op_sel_hi:[0,1]
	v_pk_fma_f32 v[18:19], v[2:3], v[122:123], v[18:19]
	v_pk_fma_f32 v[16:17], v[0:1], v[120:121], v[16:17]
	v_pk_mul_f32 v[120:121], v[64:65], v[72:73] op_sel_hi:[0,1]
	v_pk_mul_f32 v[122:123], v[64:65], v[108:109] op_sel_hi:[0,1]
	v_pk_fma_f32 v[22:23], v[6:7], v[126:127], v[22:23]
	v_pk_fma_f32 v[20:21], v[4:5], v[124:125], v[20:21]
	v_pk_fma_f32 v[26:27], v[10:11], v[130:131], v[26:27]
	v_pk_fma_f32 v[24:25], v[8:9], v[128:129], v[24:25]
	v_pk_fma_f32 v[30:31], v[14:15], v[122:123], v[30:31]
	v_pk_fma_f32 v[28:29], v[12:13], v[120:121], v[28:29]
	v_lshl_add_u64 v[120:121], v[70:71], 0, s[6:7]
	global_store_dwordx4 v[120:121], v[16:19], off nt
	global_store_dwordx4 v[120:121], v[20:23], off offset:1024 nt
	global_store_dwordx4 v[120:121], v[24:27], off offset:2048 nt
	global_store_dwordx4 v[120:121], v[28:31], off offset:3072 nt
	s_branch .LBB0_916
